# speedup vs baseline: 1.0095x; 1.0047x over previous
; #define PG8_STAGE(bufoff, gbase, voff) do { _Pragma("unroll") for (int _i = 0; _i < 2; ++_i) \
;         __builtin_amdgcn_global_load_lds((const unsigned*)((const char*)(gbase) + (voff)[_i]), (PG8_LAS unsigned*)(lds + (bufoff) + ldsw + _i * 8192), 16, 0, 0); } while (0)
; #define PG8_LDA(dst, b, h) do { _Pragma("unroll") for (int m = 0; m < 4; ++m) _Pragma("unroll") for (int k = 0; k < 2; ++k) dst[m][k] = *(const PG8_LAS bf16x8*)(lds + PG8_SA(b, h) + aoff + m * 2048 + k * 1024); } while (0)
; #define PG8_WAIT_V(n) asm volatile("s_waitcnt vmcnt(" #n ")" ::: "memory")
; #define PG8_WAIT_L(n) asm volatile("s_waitcnt lgkmcnt(" #n ")" ::: "memory")
; template <class Epi, class Sched, bool ALIGN_EPI = false, bool SP2 = false>
; __device__ __forceinline__ void gemm_phase(PG8_LAS unsigned char* lds, const Gemm g, const Sched& S, const Epi& E) {
;     ...
;         const bool has_next = S.next(ui + 1, nxt);
;         const char* nA = has_next ? (const char*)g.A + (size_t)nxt.pm * tstep : cA; const char* nB = has_next ? (const char*)g.Bt + (size_t)nxt.pn * tstep : cB;
;         for (int t = 0; t < nt; t += 2) {
;             if constexpr (Epi::MID_HOOK) { if (t == Epi::MID_T) E.mid(acc, cur, wr, wc, fr, fq); }
;             const bool last = (t == nt - 2);
;             const char* a1 = cA + (size_t)(t + 1) * kstep;
;             const char* a2 = last ? nA : cA + (size_t)(t + 2) * kstep; const char* b2 = last ? nB : cB + (size_t)(t + 2) * kstep;
;             const char* a3 = a2 + kstep; const char* b3 = b2 + kstep;
;             if (last && has_next) S.a_ready(nxt);
;             if constexpr (SP2) {
;             PG8_LDB(B0, 0, 0); PG8_LDB(B1, 0, 1); PG8_SCHED; PG8_LDA(At, 0, 0); PG8_STAGE(PG8_SA(1, 1), a1 + hstep, voffA);
;             PG8_WAIT_V(8); PG8_WAIT_L(0); PG8_BAR; PG8_MMA(0, 0, At, B0); PG8_MMA(0, 1, At, B1); PG8_BAR; PG8_SCHED;
;             PG8_LDA(At, 0, 1); PG8_STAGE(PG8_SB(0, 0), b2, voffB); PG8_STAGE(PG8_SB(0, 1), b2 + hstep, voffB); PG8_STAGE(PG8_SA(0, 0), a2, voffA);
;             PG8_WAIT_V(8); PG8_WAIT_L(0); PG8_BAR; PG8_MMA(1, 0, At, B0); PG8_MMA(1, 1, At, B1); PG8_BAR; PG8_SCHED;
;     ...
;         for (int a = 0; a < 2; ++a)
; #pragma unroll
;             for (int b = 0; b < 2; ++b)
; #pragma unroll
;                 for (int m = 0; m < 4; ++m)
; #pragma unroll
;                     for (int n = 0; n < 2; ++n) acc[a][b][m][n] = (f32x4){0.f, 0.f, 0.f, 0.f};
.LBB0_128:
	s_ashr_i32 s67, s66, 31
	s_lshl_b64 s[14:15], s[66:67], 20
	s_add_u32 s70, s37, s14
	s_addc_u32 s71, s38, s15
	s_and_b64 s[14:15], s[68:69], exec
	s_cselect_b32 s2, s71, s1
	s_cselect_b32 s11, s70, s0
	s_ashr_i32 s65, s64, 31
	s_lshl_b64 s[14:15], s[64:65], 20
	s_add_u32 s72, s31, s14
	s_addc_u32 s73, s36, s15
	s_and_b64 s[14:15], s[68:69], exec
	s_cselect_b32 s18, s73, s13
	s_cselect_b32 s19, s72, s12
	s_add_u32 s0, s0, 0x80080
	s_addc_u32 s1, s1, 0
	s_add_u32 s34, s12, 0x100
	s_addc_u32 s41, s13, 0
	s_mov_b32 s42, -2
	v_add_u32_e32 v152, 0x10000, v178
	v_add_u32_e32 v168, 0x14000, v178
	ds_read_b128 v[128:131], v152
	ds_read_b128 v[132:135], v152 offset:1024
	ds_read_b128 v[148:151], v152 offset:2048
	ds_read_b128 v[152:155], v152 offset:3072
	ds_read_b128 v[156:159], v168
	ds_read_b128 v[160:163], v168 offset:1024
	ds_read_b128 v[164:167], v168 offset:2048
	ds_read_b128 v[168:171], v168 offset:3072
	v_lshl_add_u64 v[194:195], s[0:1], 0, v[144:145]
	s_add_i32 m0, s74, 0xc000
	ds_read_b128 v[172:175], v179
	ds_read_b128 v[180:183], v179 offset:1024
	ds_read_b128 v[184:187], v179 offset:2048
	ds_read_b128 v[188:191], v179 offset:3072
	ds_read_b128 v[206:209], v179 offset:4096
	ds_read_b128 v[210:213], v179 offset:5120
	ds_read_b128 v[214:217], v179 offset:6144
	ds_read_b128 v[218:221], v179 offset:7168
	global_load_lds_dwordx4 v[194:195], off
	s_add_i32 m0, s74, 0xe000
	v_lshl_add_u64 v[194:195], s[0:1], 0, v[146:147]
	global_load_lds_dwordx4 v[194:195], off
	s_add_u32 s12, s0, 0xfff80080
	s_addc_u32 s13, s1, -1
	s_add_i32 s43, 0, 0x10000
	s_cmp_eq_u32 s42, 28
	s_cselect_b32 s15, s2, s13
	s_cselect_b32 s14, s11, s12
	s_cselect_b32 s13, s18, s41
	s_cselect_b32 s12, s19, s34
	s_add_i32 s65, 0, 0x14000
	s_waitcnt vmcnt(8)
	s_waitcnt lgkmcnt(0)
	s_barrier
	s_setprio 1
	s_waitcnt lgkmcnt(0)
	v_mfma_f32_16x16x32_bf16 v[124:127], v[128:131], v[172:175], 0
	v_mfma_f32_16x16x32_bf16 v[120:123], v[148:151], v[172:175], 0
	v_mfma_f32_16x16x32_bf16 v[108:111], v[128:131], v[184:187], 0
	v_mfma_f32_16x16x32_bf16 v[104:107], v[148:151], v[184:187], 0
	v_mfma_f32_16x16x32_bf16 v[92:95], v[128:131], v[206:209], 0
	v_mfma_f32_16x16x32_bf16 v[88:91], v[148:151], v[206:209], 0
	v_mfma_f32_16x16x32_bf16 v[76:79], v[128:131], v[214:217], 0
	v_mfma_f32_16x16x32_bf16 v[72:75], v[148:151], v[214:217], 0
	v_mfma_f32_16x16x32_bf16 v[124:127], v[132:135], v[180:183], v[124:127]
	v_mfma_f32_16x16x32_bf16 v[120:123], v[152:155], v[180:183], v[120:123]
	v_mfma_f32_16x16x32_bf16 v[108:111], v[132:135], v[188:191], v[108:111]
	v_mfma_f32_16x16x32_bf16 v[104:107], v[152:155], v[188:191], v[104:107]
	v_mfma_f32_16x16x32_bf16 v[92:95], v[132:135], v[210:213], v[92:95]
	v_mfma_f32_16x16x32_bf16 v[88:91], v[152:155], v[210:213], v[88:91]
	v_mfma_f32_16x16x32_bf16 v[76:79], v[132:135], v[218:221], v[76:79]
	v_mfma_f32_16x16x32_bf16 v[72:75], v[152:155], v[218:221], v[72:75]
	s_setprio 0
	s_setprio 1
	v_mfma_f32_16x16x32_bf16 v[116:119], v[156:159], v[172:175], 0
	v_mfma_f32_16x16x32_bf16 v[112:115], v[164:167], v[172:175], 0
	v_mfma_f32_16x16x32_bf16 v[100:103], v[156:159], v[184:187], 0
	v_mfma_f32_16x16x32_bf16 v[96:99], v[164:167], v[184:187], 0
	v_mfma_f32_16x16x32_bf16 v[84:87], v[156:159], v[206:209], 0
	v_mfma_f32_16x16x32_bf16 v[80:83], v[164:167], v[206:209], 0
	v_mfma_f32_16x16x32_bf16 v[68:71], v[156:159], v[214:217], 0
	v_mfma_f32_16x16x32_bf16 v[64:67], v[164:167], v[214:217], 0
	v_mfma_f32_16x16x32_bf16 v[116:119], v[160:163], v[180:183], v[116:119]
	v_mfma_f32_16x16x32_bf16 v[112:115], v[168:171], v[180:183], v[112:115]
	v_mfma_f32_16x16x32_bf16 v[100:103], v[160:163], v[188:191], v[100:103]
	v_mfma_f32_16x16x32_bf16 v[96:99], v[168:171], v[188:191], v[96:99]
	v_mfma_f32_16x16x32_bf16 v[84:87], v[160:163], v[210:213], v[84:87]
	v_mfma_f32_16x16x32_bf16 v[80:83], v[168:171], v[210:213], v[80:83]
	v_mfma_f32_16x16x32_bf16 v[68:71], v[160:163], v[218:221], v[68:71]
	v_mfma_f32_16x16x32_bf16 v[64:67], v[168:171], v[218:221], v[64:67]
	s_setprio 0
	s_barrier
	s_add_i32 s43, s43, s39
	v_lshl_add_u64 v[194:195], s[12:13], 0, v[138:139]
	s_mov_b32 m0, s43
	ds_read_b128 v[172:175], v179 offset:16384
	ds_read_b128 v[180:183], v179 offset:17408
	ds_read_b128 v[184:187], v179 offset:18432
	ds_read_b128 v[188:191], v179 offset:19456
	ds_read_b128 v[206:209], v179 offset:20480
	ds_read_b128 v[210:213], v179 offset:21504
	ds_read_b128 v[214:217], v179 offset:22528
	ds_read_b128 v[218:221], v179 offset:23552
	global_load_lds_dwordx4 v[194:195], off
	s_add_i32 m0, s43, 0x2000
	s_add_u32 s86, s12, 0x80000
	v_lshl_add_u64 v[196:197], s[12:13], 0, v[142:143]
	s_addc_u32 s87, s13, 0
	s_add_i32 s43, s65, s39
	global_load_lds_dwordx4 v[196:197], off
	v_lshl_add_u64 v[202:203], s[86:87], 0, v[138:139]
	s_mov_b32 m0, s43
	v_lshl_add_u64 v[204:205], s[14:15], 0, v[140:141]
	global_load_lds_dwordx4 v[202:203], off
	s_add_i32 m0, s43, 0x2000
	v_lshl_add_u64 v[202:203], s[86:87], 0, v[142:143]
	global_load_lds_dwordx4 v[202:203], off
	s_mov_b32 m0, s74
	v_lshl_add_u64 v[202:203], s[14:15], 0, v[136:137]
	global_load_lds_dwordx4 v[202:203], off
	s_mov_b32 m0, s75
	s_nop 0
	global_load_lds_dwordx4 v[204:205], off
	s_waitcnt vmcnt(8)
	s_waitcnt lgkmcnt(0)
	s_barrier
; #define PG8_STAGE(bufoff, gbase, voff) do { _Pragma("unroll") for (int _i = 0; _i < 2; ++_i) \
;         __builtin_amdgcn_global_load_lds((const unsigned*)((const char*)(gbase) + (voff)[_i]), (PG8_LAS unsigned*)(lds + (bufoff) + ldsw + _i * 8192), 16, 0, 0); } while (0)
; #define PG8_LDA(dst, b, h) do { _Pragma("unroll") for (int m = 0; m < 4; ++m) _Pragma("unroll") for (int k = 0; k < 2; ++k) dst[m][k] = *(const PG8_LAS bf16x8*)(lds + PG8_SA(b, h) + aoff + m * 2048 + k * 1024); } while (0)
; #define PG8_LDB(dst, b, h) do { _Pragma("unroll") for (int n = 0; n < 2; ++n) _Pragma("unroll") for (int k = 0; k < 2; ++k) dst[n][k] = *(const PG8_LAS bf16x8*)(lds + PG8_SB(b, h) + boff + n * 2048 + k * 1024); } while (0)
; #define PG8_MMA(ai, bj, At, Bt) do { __builtin_amdgcn_s_setprio(1); _Pragma("unroll") for (int m = 0; m < 4; ++m) _Pragma("unroll") for (int n = 0; n < 2; ++n) _Pragma("unroll") for (int k = 0; k < 2; ++k) \
;         acc[ai][bj][m][n] = __builtin_amdgcn_mfma_f32_16x16x32_bf16(Bt[n][k], At[m][k], acc[ai][bj][m][n], 0, 0, 0); __builtin_amdgcn_s_setprio(0); } while (0)
; #define PG8_WAIT_V(n) asm volatile("s_waitcnt vmcnt(" #n ")" ::: "memory")
; #define PG8_WAIT_L(n) asm volatile("s_waitcnt lgkmcnt(" #n ")" ::: "memory")
; #define PG8_BAR __builtin_amdgcn_s_barrier()
; #define PG8_SCHED __builtin_amdgcn_sched_barrier(0)
; template <class Epi, class Sched, bool ALIGN_EPI = false, bool SP2 = false>
; __device__ __forceinline__ void gemm_phase(PG8_LAS unsigned char* lds, const Gemm g, const Sched& S, const Epi& E) {
;     ...
;             PG8_WAIT_V(8); PG8_WAIT_L(0); PG8_BAR; PG8_MMA(1, 0, At, B0); PG8_MMA(1, 1, At, B1); PG8_BAR; PG8_SCHED;
;             PG8_LDB(B0, 1, 0); PG8_LDB(B1, 1, 1); PG8_SCHED; PG8_LDA(At, 1, 0); PG8_STAGE(PG8_SA(0, 1), a2 + hstep, voffA);
;             PG8_WAIT_V(8); PG8_WAIT_L(0); PG8_BAR; PG8_MMA(0, 0, At, B0); PG8_MMA(0, 1, At, B1); PG8_BAR; PG8_SCHED;
	s_setprio 1
	s_waitcnt lgkmcnt(0)
	v_mfma_f32_16x16x32_bf16 v[60:63], v[128:131], v[172:175], 0
	v_mfma_f32_16x16x32_bf16 v[56:59], v[148:151], v[172:175], 0
	v_mfma_f32_16x16x32_bf16 v[44:47], v[128:131], v[184:187], 0
	v_mfma_f32_16x16x32_bf16 v[40:43], v[148:151], v[184:187], 0
	v_mfma_f32_16x16x32_bf16 v[28:31], v[128:131], v[206:209], 0
	v_mfma_f32_16x16x32_bf16 v[24:27], v[148:151], v[206:209], 0
	v_mfma_f32_16x16x32_bf16 v[12:15], v[128:131], v[214:217], 0
	v_mfma_f32_16x16x32_bf16 v[8:11], v[148:151], v[214:217], 0
	v_mfma_f32_16x16x32_bf16 v[60:63], v[132:135], v[180:183], v[60:63]
	v_mfma_f32_16x16x32_bf16 v[56:59], v[152:155], v[180:183], v[56:59]
	v_mfma_f32_16x16x32_bf16 v[44:47], v[132:135], v[188:191], v[44:47]
	v_mfma_f32_16x16x32_bf16 v[40:43], v[152:155], v[188:191], v[40:43]
	v_mfma_f32_16x16x32_bf16 v[28:31], v[132:135], v[210:213], v[28:31]
	v_mfma_f32_16x16x32_bf16 v[24:27], v[152:155], v[210:213], v[24:27]
	v_mfma_f32_16x16x32_bf16 v[12:15], v[132:135], v[218:221], v[12:15]
	v_mfma_f32_16x16x32_bf16 v[8:11], v[152:155], v[218:221], v[8:11]
	s_setprio 0
	s_setprio 1
	v_mfma_f32_16x16x32_bf16 v[52:55], v[156:159], v[172:175], 0
	v_mfma_f32_16x16x32_bf16 v[48:51], v[164:167], v[172:175], 0
	v_mfma_f32_16x16x32_bf16 v[36:39], v[156:159], v[184:187], 0
	v_mfma_f32_16x16x32_bf16 v[32:35], v[164:167], v[184:187], 0
	v_mfma_f32_16x16x32_bf16 v[20:23], v[156:159], v[206:209], 0
	v_mfma_f32_16x16x32_bf16 v[16:19], v[164:167], v[206:209], 0
	v_mfma_f32_16x16x32_bf16 v[4:7], v[156:159], v[214:217], 0
	v_mfma_f32_16x16x32_bf16 v[0:3], v[164:167], v[214:217], 0
	v_mfma_f32_16x16x32_bf16 v[52:55], v[160:163], v[180:183], v[52:55]
	v_mfma_f32_16x16x32_bf16 v[48:51], v[168:171], v[180:183], v[48:51]
	v_mfma_f32_16x16x32_bf16 v[36:39], v[160:163], v[188:191], v[36:39]
	v_mfma_f32_16x16x32_bf16 v[32:35], v[168:171], v[188:191], v[32:35]
	v_mfma_f32_16x16x32_bf16 v[20:23], v[160:163], v[210:213], v[20:23]
	v_mfma_f32_16x16x32_bf16 v[16:19], v[168:171], v[210:213], v[16:19]
	v_mfma_f32_16x16x32_bf16 v[4:7], v[160:163], v[218:221], v[4:7]
	v_mfma_f32_16x16x32_bf16 v[0:3], v[168:171], v[218:221], v[0:3]
	s_setprio 0
	s_barrier
	s_add_i32 s43, 0, 0x18000
	s_add_i32 s65, 0, 0x1c000
	v_add_u32_e32 v152, 0x18000, v178
	v_add_u32_e32 v168, 0x1c000, v178
	ds_read_b128 v[128:131], v152
	ds_read_b128 v[132:135], v152 offset:1024
	ds_read_b128 v[148:151], v152 offset:2048
	ds_read_b128 v[152:155], v152 offset:3072
	ds_read_b128 v[156:159], v168
	ds_read_b128 v[160:163], v168 offset:1024
	ds_read_b128 v[164:167], v168 offset:2048
	ds_read_b128 v[168:171], v168 offset:3072
	s_add_u32 s14, s14, 0x80000
	s_addc_u32 s15, s15, 0
	s_mov_b32 m0, s76
	v_lshl_add_u64 v[232:233], s[14:15], 0, v[136:137]
	ds_read_b128 v[172:175], v179 offset:32768
	ds_read_b128 v[180:183], v179 offset:33792
	ds_read_b128 v[184:187], v179 offset:34816
	ds_read_b128 v[188:191], v179 offset:35840
	ds_read_b128 v[206:209], v179 offset:36864
	ds_read_b128 v[210:213], v179 offset:37888
	ds_read_b128 v[214:217], v179 offset:38912
	ds_read_b128 v[218:221], v179 offset:39936
	global_load_lds_dwordx4 v[232:233], off
	s_mov_b32 m0, s77
	v_lshl_add_u64 v[232:233], s[14:15], 0, v[140:141]
	global_load_lds_dwordx4 v[232:233], off
	s_waitcnt vmcnt(8)
	s_waitcnt lgkmcnt(0)
	s_barrier
	s_setprio 1
	s_waitcnt lgkmcnt(0)
	v_mfma_f32_16x16x32_bf16 v[124:127], v[128:131], v[172:175], v[124:127]
	v_mfma_f32_16x16x32_bf16 v[120:123], v[148:151], v[172:175], v[120:123]
	v_mfma_f32_16x16x32_bf16 v[108:111], v[128:131], v[184:187], v[108:111]
	v_mfma_f32_16x16x32_bf16 v[104:107], v[148:151], v[184:187], v[104:107]
	v_mfma_f32_16x16x32_bf16 v[92:95], v[128:131], v[206:209], v[92:95]
	v_mfma_f32_16x16x32_bf16 v[88:91], v[148:151], v[206:209], v[88:91]
	v_mfma_f32_16x16x32_bf16 v[76:79], v[128:131], v[214:217], v[76:79]
	v_mfma_f32_16x16x32_bf16 v[72:75], v[148:151], v[214:217], v[72:75]
	v_mfma_f32_16x16x32_bf16 v[124:127], v[132:135], v[180:183], v[124:127]
	v_mfma_f32_16x16x32_bf16 v[120:123], v[152:155], v[180:183], v[120:123]
	v_mfma_f32_16x16x32_bf16 v[108:111], v[132:135], v[188:191], v[108:111]
	v_mfma_f32_16x16x32_bf16 v[104:107], v[152:155], v[188:191], v[104:107]
	v_mfma_f32_16x16x32_bf16 v[92:95], v[132:135], v[210:213], v[92:95]
	v_mfma_f32_16x16x32_bf16 v[88:91], v[152:155], v[210:213], v[88:91]
	v_mfma_f32_16x16x32_bf16 v[76:79], v[132:135], v[218:221], v[76:79]
	v_mfma_f32_16x16x32_bf16 v[72:75], v[152:155], v[218:221], v[72:75]
	s_setprio 0
	s_setprio 1
	v_mfma_f32_16x16x32_bf16 v[116:119], v[156:159], v[172:175], v[116:119]
	v_mfma_f32_16x16x32_bf16 v[112:115], v[164:167], v[172:175], v[112:115]
	v_mfma_f32_16x16x32_bf16 v[100:103], v[156:159], v[184:187], v[100:103]
	v_mfma_f32_16x16x32_bf16 v[96:99], v[164:167], v[184:187], v[96:99]
	v_mfma_f32_16x16x32_bf16 v[84:87], v[156:159], v[206:209], v[84:87]
	v_mfma_f32_16x16x32_bf16 v[80:83], v[164:167], v[206:209], v[80:83]
	v_mfma_f32_16x16x32_bf16 v[68:71], v[156:159], v[214:217], v[68:71]
	v_mfma_f32_16x16x32_bf16 v[64:67], v[164:167], v[214:217], v[64:67]
	v_mfma_f32_16x16x32_bf16 v[116:119], v[160:163], v[180:183], v[116:119]
	v_mfma_f32_16x16x32_bf16 v[112:115], v[168:171], v[180:183], v[112:115]
	v_mfma_f32_16x16x32_bf16 v[100:103], v[160:163], v[188:191], v[100:103]
	v_mfma_f32_16x16x32_bf16 v[96:99], v[168:171], v[188:191], v[96:99]
	v_mfma_f32_16x16x32_bf16 v[84:87], v[160:163], v[210:213], v[84:87]
	v_mfma_f32_16x16x32_bf16 v[80:83], v[168:171], v[210:213], v[80:83]
	v_mfma_f32_16x16x32_bf16 v[68:71], v[160:163], v[218:221], v[68:71]
	v_mfma_f32_16x16x32_bf16 v[64:67], v[168:171], v[218:221], v[64:67]
	s_setprio 0
	s_barrier
; #define PG8_STAGE(bufoff, gbase, voff) do { _Pragma("unroll") for (int _i = 0; _i < 2; ++_i) \
;         __builtin_amdgcn_global_load_lds((const unsigned*)((const char*)(gbase) + (voff)[_i]), (PG8_LAS unsigned*)(lds + (bufoff) + ldsw + _i * 8192), 16, 0, 0); } while (0)
; #define PG8_LDA(dst, b, h) do { _Pragma("unroll") for (int m = 0; m < 4; ++m) _Pragma("unroll") for (int k = 0; k < 2; ++k) dst[m][k] = *(const PG8_LAS bf16x8*)(lds + PG8_SA(b, h) + aoff + m * 2048 + k * 1024); } while (0)
; #define PG8_MMA(ai, bj, At, Bt) do { __builtin_amdgcn_s_setprio(1); _Pragma("unroll") for (int m = 0; m < 4; ++m) _Pragma("unroll") for (int n = 0; n < 2; ++n) _Pragma("unroll") for (int k = 0; k < 2; ++k) \
;         acc[ai][bj][m][n] = __builtin_amdgcn_mfma_f32_16x16x32_bf16(Bt[n][k], At[m][k], acc[ai][bj][m][n], 0, 0, 0); __builtin_amdgcn_s_setprio(0); } while (0)
; #define PG8_WAIT_V(n) asm volatile("s_waitcnt vmcnt(" #n ")" ::: "memory")
; #define PG8_WAIT_L(n) asm volatile("s_waitcnt lgkmcnt(" #n ")" ::: "memory")
; #define PG8_BAR __builtin_amdgcn_s_barrier()
; #define PG8_SCHED __builtin_amdgcn_sched_barrier(0)
; template <class Epi, class Sched, bool ALIGN_EPI = false, bool SP2 = false>
; __device__ __forceinline__ void gemm_phase(PG8_LAS unsigned char* lds, const Gemm g, const Sched& S, const Epi& E) {
;     ...
;         for (int t = 0; t < nt; t += 2) {
;     ...
;             PG8_LDA(At, 1, 1); PG8_STAGE(PG8_SB(1, 0), b3, voffB); PG8_STAGE(PG8_SB(1, 1), b3 + hstep, voffB); PG8_STAGE(PG8_SA(1, 0), a3, voffA);
;             PG8_WAIT_V(8); PG8_WAIT_L(0); PG8_BAR; PG8_MMA(1, 0, At, B0); PG8_MMA(1, 1, At, B1); PG8_BAR; PG8_SCHED;
	s_add_i32 s14, s43, s39
	v_lshl_add_u64 v[194:195], v[194:195], 0, s[16:17]
	s_mov_b32 m0, s14
	ds_read_b128 v[172:175], v179 offset:49152
	ds_read_b128 v[180:183], v179 offset:50176
	ds_read_b128 v[184:187], v179 offset:51200
	ds_read_b128 v[188:191], v179 offset:52224
	ds_read_b128 v[206:209], v179 offset:53248
	ds_read_b128 v[210:213], v179 offset:54272
	ds_read_b128 v[214:217], v179 offset:55296
	ds_read_b128 v[218:221], v179 offset:56320
	global_load_lds_dwordx4 v[194:195], off
	s_add_i32 m0, s14, 0x2000
	s_add_u32 s12, s12, 0x80080
	v_lshl_add_u64 v[194:195], v[196:197], 0, s[16:17]
	s_addc_u32 s13, s13, 0
	s_add_i32 s14, s65, s39
	global_load_lds_dwordx4 v[194:195], off
	s_mov_b32 m0, s14
	v_lshl_add_u64 v[194:195], s[12:13], 0, v[138:139]
	global_load_lds_dwordx4 v[194:195], off
	s_add_i32 m0, s14, 0x2000
	v_lshl_add_u64 v[194:195], s[12:13], 0, v[142:143]
	global_load_lds_dwordx4 v[194:195], off
	s_mov_b32 m0, s80
	v_lshl_add_u64 v[194:195], v[202:203], 0, s[16:17]
	global_load_lds_dwordx4 v[194:195], off
	s_mov_b32 m0, s81
	v_lshl_add_u64 v[194:195], v[204:205], 0, s[16:17]
	global_load_lds_dwordx4 v[194:195], off
	s_waitcnt vmcnt(8)
	s_waitcnt lgkmcnt(0)
	s_barrier
	s_setprio 1
	s_waitcnt lgkmcnt(0)
	v_mfma_f32_16x16x32_bf16 v[60:63], v[128:131], v[172:175], v[60:63]
	v_mfma_f32_16x16x32_bf16 v[56:59], v[148:151], v[172:175], v[56:59]
	v_mfma_f32_16x16x32_bf16 v[44:47], v[128:131], v[184:187], v[44:47]
	v_mfma_f32_16x16x32_bf16 v[40:43], v[148:151], v[184:187], v[40:43]
	v_mfma_f32_16x16x32_bf16 v[28:31], v[128:131], v[206:209], v[28:31]
	v_mfma_f32_16x16x32_bf16 v[24:27], v[148:151], v[206:209], v[24:27]
	v_mfma_f32_16x16x32_bf16 v[12:15], v[128:131], v[214:217], v[12:15]
	v_mfma_f32_16x16x32_bf16 v[8:11], v[148:151], v[214:217], v[8:11]
	v_mfma_f32_16x16x32_bf16 v[60:63], v[132:135], v[180:183], v[60:63]
	v_mfma_f32_16x16x32_bf16 v[56:59], v[152:155], v[180:183], v[56:59]
	v_mfma_f32_16x16x32_bf16 v[44:47], v[132:135], v[188:191], v[44:47]
	v_mfma_f32_16x16x32_bf16 v[40:43], v[152:155], v[188:191], v[40:43]
	v_mfma_f32_16x16x32_bf16 v[28:31], v[132:135], v[210:213], v[28:31]
	v_mfma_f32_16x16x32_bf16 v[24:27], v[152:155], v[210:213], v[24:27]
	v_mfma_f32_16x16x32_bf16 v[12:15], v[132:135], v[218:221], v[12:15]
	v_mfma_f32_16x16x32_bf16 v[8:11], v[152:155], v[218:221], v[8:11]
	s_setprio 0
	s_setprio 1
	v_mfma_f32_16x16x32_bf16 v[52:55], v[156:159], v[172:175], v[52:55]
	v_mfma_f32_16x16x32_bf16 v[48:51], v[164:167], v[172:175], v[48:51]
	v_mfma_f32_16x16x32_bf16 v[36:39], v[156:159], v[184:187], v[36:39]
	v_mfma_f32_16x16x32_bf16 v[32:35], v[164:167], v[184:187], v[32:35]
	v_mfma_f32_16x16x32_bf16 v[20:23], v[156:159], v[206:209], v[20:23]
	v_mfma_f32_16x16x32_bf16 v[16:19], v[164:167], v[206:209], v[16:19]
	v_mfma_f32_16x16x32_bf16 v[4:7], v[156:159], v[214:217], v[4:7]
	v_mfma_f32_16x16x32_bf16 v[0:3], v[164:167], v[214:217], v[0:3]
	v_mfma_f32_16x16x32_bf16 v[52:55], v[160:163], v[180:183], v[52:55]
	v_mfma_f32_16x16x32_bf16 v[48:51], v[168:171], v[180:183], v[48:51]
	v_mfma_f32_16x16x32_bf16 v[36:39], v[160:163], v[188:191], v[36:39]
	v_mfma_f32_16x16x32_bf16 v[32:35], v[168:171], v[188:191], v[32:35]
	v_mfma_f32_16x16x32_bf16 v[20:23], v[160:163], v[210:213], v[20:23]
	v_mfma_f32_16x16x32_bf16 v[16:19], v[168:171], v[210:213], v[16:19]
	v_mfma_f32_16x16x32_bf16 v[4:7], v[160:163], v[218:221], v[4:7]
	v_mfma_f32_16x16x32_bf16 v[0:3], v[168:171], v[218:221], v[0:3]
	s_setprio 0
	s_barrier
	s_add_i32 s42, s42, 2
	s_add_u32 s0, s0, 0x100
	s_addc_u32 s1, s1, 0
	s_add_u32 s34, s34, 0x100
	s_addc_u32 s41, s41, 0
	s_cmp_gt_u32 s42, 29
	s_branch .LBB0_129

; #define PG8_STAGE(bufoff, gbase, voff) do { _Pragma("unroll") for (int _i = 0; _i < 2; ++_i) \
;         __builtin_amdgcn_global_load_lds((const unsigned*)((const char*)(gbase) + (voff)[_i]), (PG8_LAS unsigned*)(lds + (bufoff) + ldsw + _i * 8192), 16, 0, 0); } while (0)
; #define PG8_LDA(dst, b, h) do { _Pragma("unroll") for (int m = 0; m < 4; ++m) _Pragma("unroll") for (int k = 0; k < 2; ++k) dst[m][k] = *(const PG8_LAS bf16x8*)(lds + PG8_SA(b, h) + aoff + m * 2048 + k * 1024); } while (0)
; #define PG8_WAIT_V(n) asm volatile("s_waitcnt vmcnt(" #n ")" ::: "memory")
; #define PG8_WAIT_L(n) asm volatile("s_waitcnt lgkmcnt(" #n ")" ::: "memory")
; template <class Epi, class Sched, bool ALIGN_EPI = false, bool SP2 = false>
; __device__ __forceinline__ void gemm_phase(PG8_LAS unsigned char* lds, const Gemm g, const Sched& S, const Epi& E) {
;     ...
;         const bool has_next = S.next(ui + 1, nxt);
;         const char* nA = has_next ? (const char*)g.A + (size_t)nxt.pm * tstep : cA; const char* nB = has_next ? (const char*)g.Bt + (size_t)nxt.pn * tstep : cB;
;         for (int t = 0; t < nt; t += 2) {
;             if constexpr (Epi::MID_HOOK) { if (t == Epi::MID_T) E.mid(acc, cur, wr, wc, fr, fq); }
;             const bool last = (t == nt - 2);
;             const char* a1 = cA + (size_t)(t + 1) * kstep;
;             const char* a2 = last ? nA : cA + (size_t)(t + 2) * kstep; const char* b2 = last ? nB : cB + (size_t)(t + 2) * kstep;
;             const char* a3 = a2 + kstep; const char* b3 = b2 + kstep;
;             if (last && has_next) S.a_ready(nxt);
;             if constexpr (SP2) {
;             PG8_LDB(B0, 0, 0); PG8_LDB(B1, 0, 1); PG8_SCHED; PG8_LDA(At, 0, 0); PG8_STAGE(PG8_SA(1, 1), a1 + hstep, voffA);
;             PG8_WAIT_V(8); PG8_WAIT_L(0); PG8_BAR; PG8_MMA(0, 0, At, B0); PG8_MMA(0, 1, At, B1); PG8_BAR; PG8_SCHED;
;             PG8_LDA(At, 0, 1); PG8_STAGE(PG8_SB(0, 0), b2, voffB); PG8_STAGE(PG8_SB(0, 1), b2 + hstep, voffB); PG8_STAGE(PG8_SA(0, 0), a2, voffA);
;             PG8_WAIT_V(8); PG8_WAIT_L(0); PG8_BAR; PG8_MMA(1, 0, At, B0); PG8_MMA(1, 1, At, B1); PG8_BAR; PG8_SCHED;
;     ...
;         for (int a = 0; a < 2; ++a)
; #pragma unroll
;             for (int b = 0; b < 2; ++b)
; #pragma unroll
;                 for (int m = 0; m < 4; ++m)
; #pragma unroll
;                     for (int n = 0; n < 2; ++n) acc[a][b][m][n] = (f32x4){0.f, 0.f, 0.f, 0.f};
.LBB0_634:
	s_ashr_i32 s15, s14, 31
	s_lshl_b64 s[18:19], s[14:15], 20
	s_add_u32 s18, s45, s18
	s_addc_u32 s19, s46, s19
	s_and_b64 s[30:31], s[0:1], exec
	s_cselect_b32 s15, s19, s37
	s_cselect_b32 s61, s18, s36
	s_ashr_i32 s13, s12, 31
	s_lshl_b64 s[30:31], s[12:13], 20
	s_add_u32 s30, s34, s30
	s_addc_u32 s31, s44, s31
	s_and_b64 s[42:43], s[0:1], exec
	s_cselect_b32 s13, s31, s39
	s_cselect_b32 s62, s30, s38
	s_add_u32 s36, s36, 0x80080
	s_addc_u32 s37, s37, 0
	s_add_u32 s63, s38, 0x100
	s_addc_u32 s64, s39, 0
	s_mov_b32 s65, -2
	s_waitcnt lgkmcnt(0)
	v_add_u32_e32 v140, 0x10000, v172
	v_add_u32_e32 v168, 0x14000, v172
	ds_read_b128 v[128:131], v140
	ds_read_b128 v[132:135], v140 offset:1024
	ds_read_b128 v[136:139], v140 offset:2048
	ds_read_b128 v[140:143], v140 offset:3072
	ds_read_b128 v[144:147], v168
	ds_read_b128 v[148:151], v168 offset:1024
	ds_read_b128 v[164:167], v168 offset:2048
	ds_read_b128 v[174:177], v168 offset:3072
	v_lshl_add_u64 v[168:169], s[36:37], 0, v[160:161]
	s_add_i32 m0, s2, 0xc000
	ds_read_b128 v[178:181], v173
	ds_read_b128 v[182:185], v173 offset:1024
	ds_read_b128 v[186:189], v173 offset:2048
	ds_read_b128 v[194:197], v173 offset:3072
	ds_read_b128 v[202:205], v173 offset:4096
	ds_read_b128 v[206:209], v173 offset:5120
	ds_read_b128 v[210:213], v173 offset:6144
	ds_read_b128 v[214:217], v173 offset:7168
	global_load_lds_dwordx4 v[168:169], off
	s_add_i32 m0, s2, 0xe000
	v_lshl_add_u64 v[168:169], s[36:37], 0, v[162:163]
	global_load_lds_dwordx4 v[168:169], off
	s_add_u32 s24, s36, 0xfff80080
	s_addc_u32 s25, s37, -1
	s_add_i32 s33, 0, 0x10000
	s_cmp_eq_u32 s65, 28
	s_cselect_b32 s43, s15, s25
	s_cselect_b32 s42, s61, s24
	s_cselect_b32 s39, s13, s64
	s_cselect_b32 s38, s62, s63
	s_add_i32 s24, 0, 0x14000
	s_waitcnt vmcnt(8)
	s_waitcnt lgkmcnt(0)
	s_barrier
	s_setprio 1
	s_waitcnt lgkmcnt(0)
	v_mfma_f32_16x16x32_bf16 v[124:127], v[128:131], v[178:181], 0
	v_mfma_f32_16x16x32_bf16 v[120:123], v[136:139], v[178:181], 0
	v_mfma_f32_16x16x32_bf16 v[108:111], v[128:131], v[186:189], 0
	v_mfma_f32_16x16x32_bf16 v[104:107], v[136:139], v[186:189], 0
	v_mfma_f32_16x16x32_bf16 v[92:95], v[128:131], v[202:205], 0
	v_mfma_f32_16x16x32_bf16 v[88:91], v[136:139], v[202:205], 0
	v_mfma_f32_16x16x32_bf16 v[76:79], v[128:131], v[210:213], 0
	v_mfma_f32_16x16x32_bf16 v[72:75], v[136:139], v[210:213], 0
	v_mfma_f32_16x16x32_bf16 v[124:127], v[132:135], v[182:185], v[124:127]
	v_mfma_f32_16x16x32_bf16 v[120:123], v[140:143], v[182:185], v[120:123]
	v_mfma_f32_16x16x32_bf16 v[108:111], v[132:135], v[194:197], v[108:111]
	v_mfma_f32_16x16x32_bf16 v[104:107], v[140:143], v[194:197], v[104:107]
	v_mfma_f32_16x16x32_bf16 v[92:95], v[132:135], v[206:209], v[92:95]
	v_mfma_f32_16x16x32_bf16 v[88:91], v[140:143], v[206:209], v[88:91]
	v_mfma_f32_16x16x32_bf16 v[76:79], v[132:135], v[214:217], v[76:79]
	v_mfma_f32_16x16x32_bf16 v[72:75], v[140:143], v[214:217], v[72:75]
	s_setprio 0
	s_setprio 1
	v_mfma_f32_16x16x32_bf16 v[116:119], v[144:147], v[178:181], 0
	v_mfma_f32_16x16x32_bf16 v[112:115], v[164:167], v[178:181], 0
	v_mfma_f32_16x16x32_bf16 v[100:103], v[144:147], v[186:189], 0
	v_mfma_f32_16x16x32_bf16 v[96:99], v[164:167], v[186:189], 0
	v_mfma_f32_16x16x32_bf16 v[84:87], v[144:147], v[202:205], 0
	v_mfma_f32_16x16x32_bf16 v[80:83], v[164:167], v[202:205], 0
	v_mfma_f32_16x16x32_bf16 v[68:71], v[144:147], v[210:213], 0
	v_mfma_f32_16x16x32_bf16 v[64:67], v[164:167], v[210:213], 0
	v_mfma_f32_16x16x32_bf16 v[116:119], v[148:151], v[182:185], v[116:119]
	v_mfma_f32_16x16x32_bf16 v[112:115], v[174:177], v[182:185], v[112:115]
	v_mfma_f32_16x16x32_bf16 v[100:103], v[148:151], v[194:197], v[100:103]
	v_mfma_f32_16x16x32_bf16 v[96:99], v[174:177], v[194:197], v[96:99]
	v_mfma_f32_16x16x32_bf16 v[84:87], v[148:151], v[206:209], v[84:87]
	v_mfma_f32_16x16x32_bf16 v[80:83], v[174:177], v[206:209], v[80:83]
	v_mfma_f32_16x16x32_bf16 v[68:71], v[148:151], v[214:217], v[68:71]
	v_mfma_f32_16x16x32_bf16 v[64:67], v[174:177], v[214:217], v[64:67]
	s_setprio 0
	s_barrier
	s_add_i32 s25, s33, s47
	v_lshl_add_u64 v[168:169], s[38:39], 0, v[156:157]
	s_mov_b32 m0, s25
	ds_read_b128 v[178:181], v173 offset:16384
	ds_read_b128 v[182:185], v173 offset:17408
	ds_read_b128 v[186:189], v173 offset:18432
	ds_read_b128 v[194:197], v173 offset:19456
	ds_read_b128 v[202:205], v173 offset:20480
	ds_read_b128 v[206:209], v173 offset:21504
	ds_read_b128 v[210:213], v173 offset:22528
	ds_read_b128 v[214:217], v173 offset:23552
	global_load_lds_dwordx4 v[168:169], off
	s_add_i32 m0, s25, 0x2000
	s_add_u32 s66, s38, 0x80000
	v_lshl_add_u64 v[190:191], s[38:39], 0, v[152:153]
	s_addc_u32 s67, s39, 0
	s_add_i32 s24, s24, s47
	global_load_lds_dwordx4 v[190:191], off
	v_lshl_add_u64 v[218:219], s[66:67], 0, v[156:157]
	s_mov_b32 m0, s24
	v_lshl_add_u64 v[220:221], s[42:43], 0, v[154:155]
	global_load_lds_dwordx4 v[218:219], off
	s_add_i32 m0, s24, 0x2000
	v_lshl_add_u64 v[218:219], s[66:67], 0, v[152:153]
	global_load_lds_dwordx4 v[218:219], off
	s_mov_b32 m0, s2
	v_lshl_add_u64 v[218:219], s[42:43], 0, v[158:159]
	global_load_lds_dwordx4 v[218:219], off
	s_mov_b32 m0, s48
	s_nop 0
	global_load_lds_dwordx4 v[220:221], off
	s_waitcnt vmcnt(8)
	s_waitcnt lgkmcnt(0)
	s_barrier
; #define PG8_STAGE(bufoff, gbase, voff) do { _Pragma("unroll") for (int _i = 0; _i < 2; ++_i) \
;         __builtin_amdgcn_global_load_lds((const unsigned*)((const char*)(gbase) + (voff)[_i]), (PG8_LAS unsigned*)(lds + (bufoff) + ldsw + _i * 8192), 16, 0, 0); } while (0)
; #define PG8_LDA(dst, b, h) do { _Pragma("unroll") for (int m = 0; m < 4; ++m) _Pragma("unroll") for (int k = 0; k < 2; ++k) dst[m][k] = *(const PG8_LAS bf16x8*)(lds + PG8_SA(b, h) + aoff + m * 2048 + k * 1024); } while (0)
; #define PG8_LDB(dst, b, h) do { _Pragma("unroll") for (int n = 0; n < 2; ++n) _Pragma("unroll") for (int k = 0; k < 2; ++k) dst[n][k] = *(const PG8_LAS bf16x8*)(lds + PG8_SB(b, h) + boff + n * 2048 + k * 1024); } while (0)
; #define PG8_MMA(ai, bj, At, Bt) do { __builtin_amdgcn_s_setprio(1); _Pragma("unroll") for (int m = 0; m < 4; ++m) _Pragma("unroll") for (int n = 0; n < 2; ++n) _Pragma("unroll") for (int k = 0; k < 2; ++k) \
;         acc[ai][bj][m][n] = __builtin_amdgcn_mfma_f32_16x16x32_bf16(Bt[n][k], At[m][k], acc[ai][bj][m][n], 0, 0, 0); __builtin_amdgcn_s_setprio(0); } while (0)
; #define PG8_WAIT_V(n) asm volatile("s_waitcnt vmcnt(" #n ")" ::: "memory")
; #define PG8_WAIT_L(n) asm volatile("s_waitcnt lgkmcnt(" #n ")" ::: "memory")
; #define PG8_BAR __builtin_amdgcn_s_barrier()
; #define PG8_SCHED __builtin_amdgcn_sched_barrier(0)
; template <class Epi, class Sched, bool ALIGN_EPI = false, bool SP2 = false>
; __device__ __forceinline__ void gemm_phase(PG8_LAS unsigned char* lds, const Gemm g, const Sched& S, const Epi& E) {
;     ...
;             PG8_WAIT_V(8); PG8_WAIT_L(0); PG8_BAR; PG8_MMA(1, 0, At, B0); PG8_MMA(1, 1, At, B1); PG8_BAR; PG8_SCHED;
;             PG8_LDB(B0, 1, 0); PG8_LDB(B1, 1, 1); PG8_SCHED; PG8_LDA(At, 1, 0); PG8_STAGE(PG8_SA(0, 1), a2 + hstep, voffA);
;             PG8_WAIT_V(8); PG8_WAIT_L(0); PG8_BAR; PG8_MMA(0, 0, At, B0); PG8_MMA(0, 1, At, B1); PG8_BAR; PG8_SCHED;
	s_setprio 1
	s_waitcnt lgkmcnt(0)
	v_mfma_f32_16x16x32_bf16 v[60:63], v[128:131], v[178:181], 0
	v_mfma_f32_16x16x32_bf16 v[56:59], v[136:139], v[178:181], 0
	v_mfma_f32_16x16x32_bf16 v[44:47], v[128:131], v[186:189], 0
	v_mfma_f32_16x16x32_bf16 v[40:43], v[136:139], v[186:189], 0
	v_mfma_f32_16x16x32_bf16 v[28:31], v[128:131], v[202:205], 0
	v_mfma_f32_16x16x32_bf16 v[24:27], v[136:139], v[202:205], 0
	v_mfma_f32_16x16x32_bf16 v[12:15], v[128:131], v[210:213], 0
	v_mfma_f32_16x16x32_bf16 v[8:11], v[136:139], v[210:213], 0
	v_mfma_f32_16x16x32_bf16 v[60:63], v[132:135], v[182:185], v[60:63]
	v_mfma_f32_16x16x32_bf16 v[56:59], v[140:143], v[182:185], v[56:59]
	v_mfma_f32_16x16x32_bf16 v[44:47], v[132:135], v[194:197], v[44:47]
	v_mfma_f32_16x16x32_bf16 v[40:43], v[140:143], v[194:197], v[40:43]
	v_mfma_f32_16x16x32_bf16 v[28:31], v[132:135], v[206:209], v[28:31]
	v_mfma_f32_16x16x32_bf16 v[24:27], v[140:143], v[206:209], v[24:27]
	v_mfma_f32_16x16x32_bf16 v[12:15], v[132:135], v[214:217], v[12:15]
	v_mfma_f32_16x16x32_bf16 v[8:11], v[140:143], v[214:217], v[8:11]
	s_setprio 0
	s_setprio 1
	v_mfma_f32_16x16x32_bf16 v[52:55], v[144:147], v[178:181], 0
	v_mfma_f32_16x16x32_bf16 v[48:51], v[164:167], v[178:181], 0
	v_mfma_f32_16x16x32_bf16 v[36:39], v[144:147], v[186:189], 0
	v_mfma_f32_16x16x32_bf16 v[32:35], v[164:167], v[186:189], 0
	v_mfma_f32_16x16x32_bf16 v[20:23], v[144:147], v[202:205], 0
	v_mfma_f32_16x16x32_bf16 v[16:19], v[164:167], v[202:205], 0
	v_mfma_f32_16x16x32_bf16 v[4:7], v[144:147], v[210:213], 0
	v_mfma_f32_16x16x32_bf16 v[0:3], v[164:167], v[210:213], 0
	v_mfma_f32_16x16x32_bf16 v[52:55], v[148:151], v[182:185], v[52:55]
	v_mfma_f32_16x16x32_bf16 v[48:51], v[174:177], v[182:185], v[48:51]
	v_mfma_f32_16x16x32_bf16 v[36:39], v[148:151], v[194:197], v[36:39]
	v_mfma_f32_16x16x32_bf16 v[32:35], v[174:177], v[194:197], v[32:35]
	v_mfma_f32_16x16x32_bf16 v[20:23], v[148:151], v[206:209], v[20:23]
	v_mfma_f32_16x16x32_bf16 v[16:19], v[174:177], v[206:209], v[16:19]
	v_mfma_f32_16x16x32_bf16 v[4:7], v[148:151], v[214:217], v[4:7]
	v_mfma_f32_16x16x32_bf16 v[0:3], v[174:177], v[214:217], v[0:3]
	s_setprio 0
	s_barrier
	s_add_i32 s24, 0, 0x18000
	s_add_i32 s25, 0, 0x1c000
	v_add_u32_e32 v140, 0x18000, v172
	v_add_u32_e32 v174, 0x1c000, v172
	ds_read_b128 v[128:131], v140
	ds_read_b128 v[132:135], v140 offset:1024
	ds_read_b128 v[136:139], v140 offset:2048
	ds_read_b128 v[140:143], v140 offset:3072
	ds_read_b128 v[144:147], v174
	ds_read_b128 v[148:151], v174 offset:1024
	ds_read_b128 v[164:167], v174 offset:2048
	ds_read_b128 v[174:177], v174 offset:3072
	s_add_u32 s42, s42, 0x80000
	s_addc_u32 s43, s43, 0
	s_mov_b32 m0, s49
	v_lshl_add_u64 v[230:231], s[42:43], 0, v[158:159]
	ds_read_b128 v[178:181], v173 offset:32768
	ds_read_b128 v[182:185], v173 offset:33792
	ds_read_b128 v[186:189], v173 offset:34816
	ds_read_b128 v[194:197], v173 offset:35840
	ds_read_b128 v[202:205], v173 offset:36864
	ds_read_b128 v[206:209], v173 offset:37888
	ds_read_b128 v[210:213], v173 offset:38912
	ds_read_b128 v[214:217], v173 offset:39936
	global_load_lds_dwordx4 v[230:231], off
	s_mov_b32 m0, s50
	v_lshl_add_u64 v[230:231], s[42:43], 0, v[154:155]
	global_load_lds_dwordx4 v[230:231], off
	s_waitcnt vmcnt(8)
	s_waitcnt lgkmcnt(0)
	s_barrier
	s_setprio 1
	s_waitcnt lgkmcnt(0)
	v_mfma_f32_16x16x32_bf16 v[124:127], v[128:131], v[178:181], v[124:127]
	v_mfma_f32_16x16x32_bf16 v[120:123], v[136:139], v[178:181], v[120:123]
	v_mfma_f32_16x16x32_bf16 v[108:111], v[128:131], v[186:189], v[108:111]
	v_mfma_f32_16x16x32_bf16 v[104:107], v[136:139], v[186:189], v[104:107]
	v_mfma_f32_16x16x32_bf16 v[92:95], v[128:131], v[202:205], v[92:95]
	v_mfma_f32_16x16x32_bf16 v[88:91], v[136:139], v[202:205], v[88:91]
	v_mfma_f32_16x16x32_bf16 v[76:79], v[128:131], v[210:213], v[76:79]
	v_mfma_f32_16x16x32_bf16 v[72:75], v[136:139], v[210:213], v[72:75]
	v_mfma_f32_16x16x32_bf16 v[124:127], v[132:135], v[182:185], v[124:127]
	v_mfma_f32_16x16x32_bf16 v[120:123], v[140:143], v[182:185], v[120:123]
	v_mfma_f32_16x16x32_bf16 v[108:111], v[132:135], v[194:197], v[108:111]
	v_mfma_f32_16x16x32_bf16 v[104:107], v[140:143], v[194:197], v[104:107]
	v_mfma_f32_16x16x32_bf16 v[92:95], v[132:135], v[206:209], v[92:95]
	v_mfma_f32_16x16x32_bf16 v[88:91], v[140:143], v[206:209], v[88:91]
	v_mfma_f32_16x16x32_bf16 v[76:79], v[132:135], v[214:217], v[76:79]
	v_mfma_f32_16x16x32_bf16 v[72:75], v[140:143], v[214:217], v[72:75]
	s_setprio 0
	s_setprio 1
	v_mfma_f32_16x16x32_bf16 v[116:119], v[144:147], v[178:181], v[116:119]
	v_mfma_f32_16x16x32_bf16 v[112:115], v[164:167], v[178:181], v[112:115]
	v_mfma_f32_16x16x32_bf16 v[100:103], v[144:147], v[186:189], v[100:103]
	v_mfma_f32_16x16x32_bf16 v[96:99], v[164:167], v[186:189], v[96:99]
	v_mfma_f32_16x16x32_bf16 v[84:87], v[144:147], v[202:205], v[84:87]
	v_mfma_f32_16x16x32_bf16 v[80:83], v[164:167], v[202:205], v[80:83]
	v_mfma_f32_16x16x32_bf16 v[68:71], v[144:147], v[210:213], v[68:71]
	v_mfma_f32_16x16x32_bf16 v[64:67], v[164:167], v[210:213], v[64:67]
	v_mfma_f32_16x16x32_bf16 v[116:119], v[148:151], v[182:185], v[116:119]
	v_mfma_f32_16x16x32_bf16 v[112:115], v[174:177], v[182:185], v[112:115]
	v_mfma_f32_16x16x32_bf16 v[100:103], v[148:151], v[194:197], v[100:103]
	v_mfma_f32_16x16x32_bf16 v[96:99], v[174:177], v[194:197], v[96:99]
	v_mfma_f32_16x16x32_bf16 v[84:87], v[148:151], v[206:209], v[84:87]
	v_mfma_f32_16x16x32_bf16 v[80:83], v[174:177], v[206:209], v[80:83]
	v_mfma_f32_16x16x32_bf16 v[68:71], v[148:151], v[214:217], v[68:71]
	v_mfma_f32_16x16x32_bf16 v[64:67], v[174:177], v[214:217], v[64:67]
	s_setprio 0
	s_barrier
; #define PG8_STAGE(bufoff, gbase, voff) do { _Pragma("unroll") for (int _i = 0; _i < 2; ++_i) \
;         __builtin_amdgcn_global_load_lds((const unsigned*)((const char*)(gbase) + (voff)[_i]), (PG8_LAS unsigned*)(lds + (bufoff) + ldsw + _i * 8192), 16, 0, 0); } while (0)
; #define PG8_LDA(dst, b, h) do { _Pragma("unroll") for (int m = 0; m < 4; ++m) _Pragma("unroll") for (int k = 0; k < 2; ++k) dst[m][k] = *(const PG8_LAS bf16x8*)(lds + PG8_SA(b, h) + aoff + m * 2048 + k * 1024); } while (0)
; #define PG8_MMA(ai, bj, At, Bt) do { __builtin_amdgcn_s_setprio(1); _Pragma("unroll") for (int m = 0; m < 4; ++m) _Pragma("unroll") for (int n = 0; n < 2; ++n) _Pragma("unroll") for (int k = 0; k < 2; ++k) \
;         acc[ai][bj][m][n] = __builtin_amdgcn_mfma_f32_16x16x32_bf16(Bt[n][k], At[m][k], acc[ai][bj][m][n], 0, 0, 0); __builtin_amdgcn_s_setprio(0); } while (0)
; #define PG8_WAIT_V(n) asm volatile("s_waitcnt vmcnt(" #n ")" ::: "memory")
; #define PG8_WAIT_L(n) asm volatile("s_waitcnt lgkmcnt(" #n ")" ::: "memory")
; #define PG8_BAR __builtin_amdgcn_s_barrier()
; #define PG8_SCHED __builtin_amdgcn_sched_barrier(0)
; template <class Epi, class Sched, bool ALIGN_EPI = false, bool SP2 = false>
; __device__ __forceinline__ void gemm_phase(PG8_LAS unsigned char* lds, const Gemm g, const Sched& S, const Epi& E) {
;     ...
;             PG8_LDA(At, 1, 1); PG8_STAGE(PG8_SB(1, 0), b3, voffB); PG8_STAGE(PG8_SB(1, 1), b3 + hstep, voffB); PG8_STAGE(PG8_SA(1, 0), a3, voffA);
;             PG8_WAIT_V(8); PG8_WAIT_L(0); PG8_BAR; PG8_MMA(1, 0, At, B0); PG8_MMA(1, 1, At, B1); PG8_BAR; PG8_SCHED;
	s_add_i32 s24, s24, s47
	v_lshl_add_u64 v[168:169], v[168:169], 0, s[16:17]
	s_mov_b32 m0, s24
	ds_read_b128 v[178:181], v173 offset:49152
	ds_read_b128 v[182:185], v173 offset:50176
	ds_read_b128 v[186:189], v173 offset:51200
	ds_read_b128 v[194:197], v173 offset:52224
	ds_read_b128 v[202:205], v173 offset:53248
	ds_read_b128 v[206:209], v173 offset:54272
	ds_read_b128 v[210:213], v173 offset:55296
	ds_read_b128 v[214:217], v173 offset:56320
	global_load_lds_dwordx4 v[168:169], off
	s_add_i32 m0, s24, 0x2000
	s_add_u32 s38, s38, 0x80080
	v_lshl_add_u64 v[168:169], v[190:191], 0, s[16:17]
	s_addc_u32 s39, s39, 0
	s_add_i32 s24, s25, s47
	global_load_lds_dwordx4 v[168:169], off
	s_mov_b32 m0, s24
	v_lshl_add_u64 v[168:169], s[38:39], 0, v[156:157]
	global_load_lds_dwordx4 v[168:169], off
	s_add_i32 m0, s24, 0x2000
	v_lshl_add_u64 v[168:169], s[38:39], 0, v[152:153]
	global_load_lds_dwordx4 v[168:169], off
	s_mov_b32 m0, s55
	v_lshl_add_u64 v[168:169], v[218:219], 0, s[16:17]
	global_load_lds_dwordx4 v[168:169], off
	s_mov_b32 m0, s56
	v_lshl_add_u64 v[168:169], v[220:221], 0, s[16:17]
	global_load_lds_dwordx4 v[168:169], off
	s_waitcnt vmcnt(8)
	s_waitcnt lgkmcnt(0)
	s_barrier
	s_setprio 1
	s_waitcnt lgkmcnt(0)
	v_mfma_f32_16x16x32_bf16 v[60:63], v[128:131], v[178:181], v[60:63]
	v_mfma_f32_16x16x32_bf16 v[56:59], v[136:139], v[178:181], v[56:59]
	v_mfma_f32_16x16x32_bf16 v[44:47], v[128:131], v[186:189], v[44:47]
	v_mfma_f32_16x16x32_bf16 v[40:43], v[136:139], v[186:189], v[40:43]
	v_mfma_f32_16x16x32_bf16 v[28:31], v[128:131], v[202:205], v[28:31]
	v_mfma_f32_16x16x32_bf16 v[24:27], v[136:139], v[202:205], v[24:27]
	v_mfma_f32_16x16x32_bf16 v[12:15], v[128:131], v[210:213], v[12:15]
	v_mfma_f32_16x16x32_bf16 v[8:11], v[136:139], v[210:213], v[8:11]
	v_mfma_f32_16x16x32_bf16 v[60:63], v[132:135], v[182:185], v[60:63]
	v_mfma_f32_16x16x32_bf16 v[56:59], v[140:143], v[182:185], v[56:59]
	v_mfma_f32_16x16x32_bf16 v[44:47], v[132:135], v[194:197], v[44:47]
	v_mfma_f32_16x16x32_bf16 v[40:43], v[140:143], v[194:197], v[40:43]
	v_mfma_f32_16x16x32_bf16 v[28:31], v[132:135], v[206:209], v[28:31]
	v_mfma_f32_16x16x32_bf16 v[24:27], v[140:143], v[206:209], v[24:27]
	v_mfma_f32_16x16x32_bf16 v[12:15], v[132:135], v[214:217], v[12:15]
	v_mfma_f32_16x16x32_bf16 v[8:11], v[140:143], v[214:217], v[8:11]
	s_setprio 0
	s_setprio 1
	v_mfma_f32_16x16x32_bf16 v[52:55], v[144:147], v[178:181], v[52:55]
	v_mfma_f32_16x16x32_bf16 v[48:51], v[164:167], v[178:181], v[48:51]
	v_mfma_f32_16x16x32_bf16 v[36:39], v[144:147], v[186:189], v[36:39]
	v_mfma_f32_16x16x32_bf16 v[32:35], v[164:167], v[186:189], v[32:35]
	v_mfma_f32_16x16x32_bf16 v[20:23], v[144:147], v[202:205], v[20:23]
	v_mfma_f32_16x16x32_bf16 v[16:19], v[164:167], v[202:205], v[16:19]
	v_mfma_f32_16x16x32_bf16 v[4:7], v[144:147], v[210:213], v[4:7]
	v_mfma_f32_16x16x32_bf16 v[0:3], v[164:167], v[210:213], v[0:3]
	v_mfma_f32_16x16x32_bf16 v[52:55], v[148:151], v[182:185], v[52:55]
	v_mfma_f32_16x16x32_bf16 v[48:51], v[174:177], v[182:185], v[48:51]
	v_mfma_f32_16x16x32_bf16 v[36:39], v[148:151], v[194:197], v[36:39]
	v_mfma_f32_16x16x32_bf16 v[32:35], v[174:177], v[194:197], v[32:35]
	v_mfma_f32_16x16x32_bf16 v[20:23], v[148:151], v[206:209], v[20:23]
	v_mfma_f32_16x16x32_bf16 v[16:19], v[174:177], v[206:209], v[16:19]
	v_mfma_f32_16x16x32_bf16 v[4:7], v[148:151], v[214:217], v[4:7]
	v_mfma_f32_16x16x32_bf16 v[0:3], v[174:177], v[214:217], v[0:3]
	s_setprio 0
	s_barrier
	s_add_i32 s65, s65, 2
	s_add_u32 s36, s36, 0x100
	s_addc_u32 s37, s37, 0
	s_add_u32 s63, s63, 0x100
	s_addc_u32 s64, s64, 0
	s_cmp_gt_u32 s65, 29
	s_branch .LBB0_635

; #define PG8_STAGE(bufoff, gbase, voff) do { _Pragma("unroll") for (int _i = 0; _i < 2; ++_i) \
;         __builtin_amdgcn_global_load_lds((const unsigned*)((const char*)(gbase) + (voff)[_i]), (PG8_LAS unsigned*)(lds + (bufoff) + ldsw + _i * 8192), 16, 0, 0); } while (0)
; #define PG8_LDA(dst, b, h) do { _Pragma("unroll") for (int m = 0; m < 4; ++m) _Pragma("unroll") for (int k = 0; k < 2; ++k) dst[m][k] = *(const PG8_LAS bf16x8*)(lds + PG8_SA(b, h) + aoff + m * 2048 + k * 1024); } while (0)
; #define PG8_WAIT_V(n) asm volatile("s_waitcnt vmcnt(" #n ")" ::: "memory")
; #define PG8_WAIT_L(n) asm volatile("s_waitcnt lgkmcnt(" #n ")" ::: "memory")
; template <class Epi, class Sched, bool ALIGN_EPI = false, bool SP2 = false>
; __device__ __forceinline__ void gemm_phase(PG8_LAS unsigned char* lds, const Gemm g, const Sched& S, const Epi& E) {
;     ...
;         const bool has_next = S.next(ui + 1, nxt);
;         const char* nA = has_next ? (const char*)g.A + (size_t)nxt.pm * tstep : cA; const char* nB = has_next ? (const char*)g.Bt + (size_t)nxt.pn * tstep : cB;
;         for (int t = 0; t < nt; t += 2) {
;             if constexpr (Epi::MID_HOOK) { if (t == Epi::MID_T) E.mid(acc, cur, wr, wc, fr, fq); }
;             const bool last = (t == nt - 2);
;             const char* a1 = cA + (size_t)(t + 1) * kstep;
;             const char* a2 = last ? nA : cA + (size_t)(t + 2) * kstep; const char* b2 = last ? nB : cB + (size_t)(t + 2) * kstep;
;             const char* a3 = a2 + kstep; const char* b3 = b2 + kstep;
;             if (last && has_next) S.a_ready(nxt);
;             if constexpr (SP2) {
;             PG8_LDB(B0, 0, 0); PG8_LDB(B1, 0, 1); PG8_SCHED; PG8_LDA(At, 0, 0); PG8_STAGE(PG8_SA(1, 1), a1 + hstep, voffA);
;             PG8_WAIT_V(8); PG8_WAIT_L(0); PG8_BAR; PG8_MMA(0, 0, At, B0); PG8_MMA(0, 1, At, B1); PG8_BAR; PG8_SCHED;
;             PG8_LDA(At, 0, 1); PG8_STAGE(PG8_SB(0, 0), b2, voffB); PG8_STAGE(PG8_SB(0, 1), b2 + hstep, voffB); PG8_STAGE(PG8_SA(0, 0), a2, voffA);
;             PG8_WAIT_V(8); PG8_WAIT_L(0); PG8_BAR; PG8_MMA(1, 0, At, B0); PG8_MMA(1, 1, At, B1); PG8_BAR; PG8_SCHED;
;     ...
;         for (int a = 0; a < 2; ++a)
; #pragma unroll
;             for (int b = 0; b < 2; ++b)
; #pragma unroll
;                 for (int m = 0; m < 4; ++m)
; #pragma unroll
;                     for (int n = 0; n < 2; ++n) acc[a][b][m][n] = (f32x4){0.f, 0.f, 0.f, 0.f};
.LBB0_729:
	s_ashr_i32 s49, s48, 31
	s_lshl_b64 s[12:13], s[48:49], 20
	s_add_u32 s50, s18, s12
	s_addc_u32 s51, s19, s13
	s_and_b64 s[12:13], s[42:43], exec
	s_cselect_b32 s49, s51, s1
	s_cselect_b32 s60, s50, s0
	s_ashr_i32 s47, s46, 31
	s_lshl_b64 s[12:13], s[46:47], 20
	s_add_u32 s52, s14, s12
	s_addc_u32 s53, s15, s13
	s_and_b64 s[12:13], s[42:43], exec
	s_cselect_b32 s47, s53, s11
	s_cselect_b32 s61, s52, s10
	s_add_u32 s0, s0, 0x80080
	s_addc_u32 s1, s1, 0
	s_add_u32 s62, s10, 0x100
	s_addc_u32 s63, s11, 0
	s_mov_b32 s64, -2
	v_add_u32_e32 v148, 0x10000, v151
	ds_read_b128 v[140:143], v148
	ds_read_b128 v[144:147], v148 offset:1024
	ds_read_b128 v[154:157], v148 offset:2048
	ds_read_b128 v[158:161], v148 offset:3072
	v_add_u32_e32 v148, 0x14000, v151
	ds_read_b128 v[162:165], v148
	ds_read_b128 v[166:169], v148 offset:1024
	ds_read_b128 v[170:173], v148 offset:2048
	ds_read_b128 v[174:177], v148 offset:3072
	v_lshl_add_u64 v[190:191], s[0:1], 0, v[136:137]
	s_add_i32 m0, s31, 0xc000
	ds_read_b128 v[178:181], v152
	ds_read_b128 v[182:185], v152 offset:1024
	ds_read_b128 v[186:189], v152 offset:2048
	ds_read_b128 v[194:197], v152 offset:3072
	ds_read_b128 v[202:205], v152 offset:4096
	ds_read_b128 v[206:209], v152 offset:5120
	ds_read_b128 v[210:213], v152 offset:6144
	ds_read_b128 v[214:217], v152 offset:7168
	global_load_lds_dwordx4 v[190:191], off
	s_add_i32 m0, s31, 0xe000
	v_lshl_add_u64 v[190:191], s[0:1], 0, v[138:139]
	global_load_lds_dwordx4 v[190:191], off
	s_add_u32 s10, s0, 0xfff80080
	s_addc_u32 s11, s1, -1
	s_add_i32 s24, 0, 0x10000
	s_cmp_eq_u32 s64, 28
	s_cselect_b32 s13, s49, s11
	s_cselect_b32 s12, s60, s10
	s_cselect_b32 s11, s47, s63
	s_cselect_b32 s10, s61, s62
	s_add_i32 s25, 0, 0x14000
	s_waitcnt vmcnt(8)
	s_waitcnt lgkmcnt(0)
	s_barrier
	s_setprio 1
	s_waitcnt lgkmcnt(0)
	v_mfma_f32_16x16x32_bf16 v[124:127], v[140:143], v[178:181], 0
	v_mfma_f32_16x16x32_bf16 v[112:115], v[154:157], v[178:181], 0
	v_mfma_f32_16x16x32_bf16 v[108:111], v[140:143], v[186:189], 0
	v_mfma_f32_16x16x32_bf16 v[100:103], v[154:157], v[186:189], 0
	v_mfma_f32_16x16x32_bf16 v[92:95], v[140:143], v[202:205], 0
	v_mfma_f32_16x16x32_bf16 v[84:87], v[154:157], v[202:205], 0
	v_mfma_f32_16x16x32_bf16 v[76:79], v[140:143], v[210:213], 0
	v_mfma_f32_16x16x32_bf16 v[68:71], v[154:157], v[210:213], 0
	v_mfma_f32_16x16x32_bf16 v[124:127], v[144:147], v[182:185], v[124:127]
	v_mfma_f32_16x16x32_bf16 v[112:115], v[158:161], v[182:185], v[112:115]
	v_mfma_f32_16x16x32_bf16 v[108:111], v[144:147], v[194:197], v[108:111]
	v_mfma_f32_16x16x32_bf16 v[100:103], v[158:161], v[194:197], v[100:103]
	v_mfma_f32_16x16x32_bf16 v[92:95], v[144:147], v[206:209], v[92:95]
	v_mfma_f32_16x16x32_bf16 v[84:87], v[158:161], v[206:209], v[84:87]
	v_mfma_f32_16x16x32_bf16 v[76:79], v[144:147], v[214:217], v[76:79]
	v_mfma_f32_16x16x32_bf16 v[68:71], v[158:161], v[214:217], v[68:71]
	s_setprio 0
	s_setprio 1
	v_mfma_f32_16x16x32_bf16 v[120:123], v[162:165], v[178:181], 0
	v_mfma_f32_16x16x32_bf16 v[116:119], v[170:173], v[178:181], 0
	v_mfma_f32_16x16x32_bf16 v[104:107], v[162:165], v[186:189], 0
	v_mfma_f32_16x16x32_bf16 v[96:99], v[170:173], v[186:189], 0
	v_mfma_f32_16x16x32_bf16 v[88:91], v[162:165], v[202:205], 0
	v_mfma_f32_16x16x32_bf16 v[80:83], v[170:173], v[202:205], 0
	v_mfma_f32_16x16x32_bf16 v[72:75], v[162:165], v[210:213], 0
	v_mfma_f32_16x16x32_bf16 v[64:67], v[170:173], v[210:213], 0
	v_mfma_f32_16x16x32_bf16 v[120:123], v[166:169], v[182:185], v[120:123]
	v_mfma_f32_16x16x32_bf16 v[116:119], v[174:177], v[182:185], v[116:119]
	v_mfma_f32_16x16x32_bf16 v[104:107], v[166:169], v[194:197], v[104:107]
	v_mfma_f32_16x16x32_bf16 v[96:99], v[174:177], v[194:197], v[96:99]
	v_mfma_f32_16x16x32_bf16 v[88:91], v[166:169], v[206:209], v[88:91]
	v_mfma_f32_16x16x32_bf16 v[80:83], v[174:177], v[206:209], v[80:83]
	v_mfma_f32_16x16x32_bf16 v[72:75], v[166:169], v[214:217], v[72:75]
	v_mfma_f32_16x16x32_bf16 v[64:67], v[174:177], v[214:217], v[64:67]
	s_setprio 0
	s_barrier
	s_add_i32 s24, s24, s30
	v_lshl_add_u64 v[190:191], s[10:11], 0, v[132:133]
	s_mov_b32 m0, s24
	ds_read_b128 v[178:181], v152 offset:16384
	ds_read_b128 v[182:185], v152 offset:17408
	ds_read_b128 v[186:189], v152 offset:18432
	ds_read_b128 v[194:197], v152 offset:19456
	ds_read_b128 v[202:205], v152 offset:20480
	ds_read_b128 v[206:209], v152 offset:21504
	ds_read_b128 v[210:213], v152 offset:22528
	ds_read_b128 v[214:217], v152 offset:23552
	global_load_lds_dwordx4 v[190:191], off
	s_add_i32 m0, s24, 0x2000
	s_add_u32 s66, s10, 0x80000
	v_lshl_add_u64 v[218:219], s[10:11], 0, v[128:129]
	s_addc_u32 s67, s11, 0
	s_add_i32 s24, s25, s30
	global_load_lds_dwordx4 v[218:219], off
	v_lshl_add_u64 v[220:221], s[66:67], 0, v[132:133]
	s_mov_b32 m0, s24
	v_lshl_add_u64 v[230:231], s[12:13], 0, v[130:131]
	global_load_lds_dwordx4 v[220:221], off
	s_add_i32 m0, s24, 0x2000
	v_lshl_add_u64 v[220:221], s[66:67], 0, v[128:129]
	global_load_lds_dwordx4 v[220:221], off
	s_mov_b32 m0, s31
	v_lshl_add_u64 v[220:221], s[12:13], 0, v[134:135]
	global_load_lds_dwordx4 v[220:221], off
	s_mov_b32 m0, s34
	s_nop 0
	global_load_lds_dwordx4 v[230:231], off
	s_waitcnt vmcnt(8)
	s_waitcnt lgkmcnt(0)
	s_barrier
; #define PG8_STAGE(bufoff, gbase, voff) do { _Pragma("unroll") for (int _i = 0; _i < 2; ++_i) \
;         __builtin_amdgcn_global_load_lds((const unsigned*)((const char*)(gbase) + (voff)[_i]), (PG8_LAS unsigned*)(lds + (bufoff) + ldsw + _i * 8192), 16, 0, 0); } while (0)
; #define PG8_LDA(dst, b, h) do { _Pragma("unroll") for (int m = 0; m < 4; ++m) _Pragma("unroll") for (int k = 0; k < 2; ++k) dst[m][k] = *(const PG8_LAS bf16x8*)(lds + PG8_SA(b, h) + aoff + m * 2048 + k * 1024); } while (0)
; #define PG8_LDB(dst, b, h) do { _Pragma("unroll") for (int n = 0; n < 2; ++n) _Pragma("unroll") for (int k = 0; k < 2; ++k) dst[n][k] = *(const PG8_LAS bf16x8*)(lds + PG8_SB(b, h) + boff + n * 2048 + k * 1024); } while (0)
; #define PG8_MMA(ai, bj, At, Bt) do { __builtin_amdgcn_s_setprio(1); _Pragma("unroll") for (int m = 0; m < 4; ++m) _Pragma("unroll") for (int n = 0; n < 2; ++n) _Pragma("unroll") for (int k = 0; k < 2; ++k) \
;         acc[ai][bj][m][n] = __builtin_amdgcn_mfma_f32_16x16x32_bf16(Bt[n][k], At[m][k], acc[ai][bj][m][n], 0, 0, 0); __builtin_amdgcn_s_setprio(0); } while (0)
; #define PG8_WAIT_V(n) asm volatile("s_waitcnt vmcnt(" #n ")" ::: "memory")
; #define PG8_WAIT_L(n) asm volatile("s_waitcnt lgkmcnt(" #n ")" ::: "memory")
; #define PG8_BAR __builtin_amdgcn_s_barrier()
; #define PG8_SCHED __builtin_amdgcn_sched_barrier(0)
; template <class Epi, class Sched, bool ALIGN_EPI = false, bool SP2 = false>
; __device__ __forceinline__ void gemm_phase(PG8_LAS unsigned char* lds, const Gemm g, const Sched& S, const Epi& E) {
;     ...
;             PG8_WAIT_V(8); PG8_WAIT_L(0); PG8_BAR; PG8_MMA(1, 0, At, B0); PG8_MMA(1, 1, At, B1); PG8_BAR; PG8_SCHED;
;             PG8_LDB(B0, 1, 0); PG8_LDB(B1, 1, 1); PG8_SCHED; PG8_LDA(At, 1, 0); PG8_STAGE(PG8_SA(0, 1), a2 + hstep, voffA);
;             PG8_WAIT_V(8); PG8_WAIT_L(0); PG8_BAR; PG8_MMA(0, 0, At, B0); PG8_MMA(0, 1, At, B1); PG8_BAR; PG8_SCHED;
	s_setprio 1
	s_waitcnt lgkmcnt(0)
	v_mfma_f32_16x16x32_bf16 v[60:63], v[140:143], v[178:181], 0
	v_mfma_f32_16x16x32_bf16 v[52:55], v[154:157], v[178:181], 0
	v_mfma_f32_16x16x32_bf16 v[44:47], v[140:143], v[186:189], 0
	v_mfma_f32_16x16x32_bf16 v[36:39], v[154:157], v[186:189], 0
	v_mfma_f32_16x16x32_bf16 v[28:31], v[140:143], v[202:205], 0
	v_mfma_f32_16x16x32_bf16 v[20:23], v[154:157], v[202:205], 0
	v_mfma_f32_16x16x32_bf16 v[12:15], v[140:143], v[210:213], 0
	v_mfma_f32_16x16x32_bf16 v[4:7], v[154:157], v[210:213], 0
	v_mfma_f32_16x16x32_bf16 v[60:63], v[144:147], v[182:185], v[60:63]
	v_mfma_f32_16x16x32_bf16 v[52:55], v[158:161], v[182:185], v[52:55]
	v_mfma_f32_16x16x32_bf16 v[44:47], v[144:147], v[194:197], v[44:47]
	v_mfma_f32_16x16x32_bf16 v[36:39], v[158:161], v[194:197], v[36:39]
	v_mfma_f32_16x16x32_bf16 v[28:31], v[144:147], v[206:209], v[28:31]
	v_mfma_f32_16x16x32_bf16 v[20:23], v[158:161], v[206:209], v[20:23]
	v_mfma_f32_16x16x32_bf16 v[12:15], v[144:147], v[214:217], v[12:15]
	v_mfma_f32_16x16x32_bf16 v[4:7], v[158:161], v[214:217], v[4:7]
	s_setprio 0
	s_setprio 1
	v_mfma_f32_16x16x32_bf16 v[56:59], v[162:165], v[178:181], 0
	v_mfma_f32_16x16x32_bf16 v[48:51], v[170:173], v[178:181], 0
	v_mfma_f32_16x16x32_bf16 v[40:43], v[162:165], v[186:189], 0
	v_mfma_f32_16x16x32_bf16 v[32:35], v[170:173], v[186:189], 0
	v_mfma_f32_16x16x32_bf16 v[24:27], v[162:165], v[202:205], 0
	v_mfma_f32_16x16x32_bf16 v[16:19], v[170:173], v[202:205], 0
	v_mfma_f32_16x16x32_bf16 v[8:11], v[162:165], v[210:213], 0
	v_mfma_f32_16x16x32_bf16 v[0:3], v[170:173], v[210:213], 0
	v_mfma_f32_16x16x32_bf16 v[56:59], v[166:169], v[182:185], v[56:59]
	v_mfma_f32_16x16x32_bf16 v[48:51], v[174:177], v[182:185], v[48:51]
	v_mfma_f32_16x16x32_bf16 v[40:43], v[166:169], v[194:197], v[40:43]
	v_mfma_f32_16x16x32_bf16 v[32:35], v[174:177], v[194:197], v[32:35]
	v_mfma_f32_16x16x32_bf16 v[24:27], v[166:169], v[206:209], v[24:27]
	v_mfma_f32_16x16x32_bf16 v[16:19], v[174:177], v[206:209], v[16:19]
	v_mfma_f32_16x16x32_bf16 v[8:11], v[166:169], v[214:217], v[8:11]
	v_mfma_f32_16x16x32_bf16 v[0:3], v[174:177], v[214:217], v[0:3]
	s_setprio 0
	s_barrier
	s_add_i32 s24, 0, 0x18000
	v_add_u32_e32 v148, 0x18000, v151
	s_add_i32 s25, 0, 0x1c000
	ds_read_b128 v[140:143], v148
	ds_read_b128 v[144:147], v148 offset:1024
	ds_read_b128 v[154:157], v148 offset:2048
	ds_read_b128 v[158:161], v148 offset:3072
	v_add_u32_e32 v148, 0x1c000, v151
	ds_read_b128 v[162:165], v148
	ds_read_b128 v[166:169], v148 offset:1024
	ds_read_b128 v[170:173], v148 offset:2048
	ds_read_b128 v[174:177], v148 offset:3072
	s_add_u32 s12, s12, 0x80000
	s_addc_u32 s13, s13, 0
	s_mov_b32 m0, s36
	v_lshl_add_u64 v[232:233], s[12:13], 0, v[134:135]
	ds_read_b128 v[178:181], v152 offset:32768
	ds_read_b128 v[182:185], v152 offset:33792
	ds_read_b128 v[186:189], v152 offset:34816
	ds_read_b128 v[194:197], v152 offset:35840
	ds_read_b128 v[202:205], v152 offset:36864
	ds_read_b128 v[206:209], v152 offset:37888
	ds_read_b128 v[210:213], v152 offset:38912
	ds_read_b128 v[214:217], v152 offset:39936
	global_load_lds_dwordx4 v[232:233], off
	s_mov_b32 m0, s37
	v_lshl_add_u64 v[232:233], s[12:13], 0, v[130:131]
	global_load_lds_dwordx4 v[232:233], off
	s_waitcnt vmcnt(8)
	s_waitcnt lgkmcnt(0)
	s_barrier
	s_setprio 1
	s_waitcnt lgkmcnt(0)
	v_mfma_f32_16x16x32_bf16 v[124:127], v[140:143], v[178:181], v[124:127]
	v_mfma_f32_16x16x32_bf16 v[112:115], v[154:157], v[178:181], v[112:115]
	v_mfma_f32_16x16x32_bf16 v[108:111], v[140:143], v[186:189], v[108:111]
	v_mfma_f32_16x16x32_bf16 v[100:103], v[154:157], v[186:189], v[100:103]
	v_mfma_f32_16x16x32_bf16 v[92:95], v[140:143], v[202:205], v[92:95]
	v_mfma_f32_16x16x32_bf16 v[84:87], v[154:157], v[202:205], v[84:87]
	v_mfma_f32_16x16x32_bf16 v[76:79], v[140:143], v[210:213], v[76:79]
	v_mfma_f32_16x16x32_bf16 v[68:71], v[154:157], v[210:213], v[68:71]
	v_mfma_f32_16x16x32_bf16 v[124:127], v[144:147], v[182:185], v[124:127]
	v_mfma_f32_16x16x32_bf16 v[112:115], v[158:161], v[182:185], v[112:115]
	v_mfma_f32_16x16x32_bf16 v[108:111], v[144:147], v[194:197], v[108:111]
	v_mfma_f32_16x16x32_bf16 v[100:103], v[158:161], v[194:197], v[100:103]
	v_mfma_f32_16x16x32_bf16 v[92:95], v[144:147], v[206:209], v[92:95]
	v_mfma_f32_16x16x32_bf16 v[84:87], v[158:161], v[206:209], v[84:87]
	v_mfma_f32_16x16x32_bf16 v[76:79], v[144:147], v[214:217], v[76:79]
	v_mfma_f32_16x16x32_bf16 v[68:71], v[158:161], v[214:217], v[68:71]
	s_setprio 0
	s_setprio 1
	v_mfma_f32_16x16x32_bf16 v[120:123], v[162:165], v[178:181], v[120:123]
	v_mfma_f32_16x16x32_bf16 v[116:119], v[170:173], v[178:181], v[116:119]
	v_mfma_f32_16x16x32_bf16 v[104:107], v[162:165], v[186:189], v[104:107]
	v_mfma_f32_16x16x32_bf16 v[96:99], v[170:173], v[186:189], v[96:99]
	v_mfma_f32_16x16x32_bf16 v[88:91], v[162:165], v[202:205], v[88:91]
	v_mfma_f32_16x16x32_bf16 v[80:83], v[170:173], v[202:205], v[80:83]
	v_mfma_f32_16x16x32_bf16 v[72:75], v[162:165], v[210:213], v[72:75]
	v_mfma_f32_16x16x32_bf16 v[64:67], v[170:173], v[210:213], v[64:67]
	v_mfma_f32_16x16x32_bf16 v[120:123], v[166:169], v[182:185], v[120:123]
	v_mfma_f32_16x16x32_bf16 v[116:119], v[174:177], v[182:185], v[116:119]
	v_mfma_f32_16x16x32_bf16 v[104:107], v[166:169], v[194:197], v[104:107]
	v_mfma_f32_16x16x32_bf16 v[96:99], v[174:177], v[194:197], v[96:99]
	v_mfma_f32_16x16x32_bf16 v[88:91], v[166:169], v[206:209], v[88:91]
	v_mfma_f32_16x16x32_bf16 v[80:83], v[174:177], v[206:209], v[80:83]
	v_mfma_f32_16x16x32_bf16 v[72:75], v[166:169], v[214:217], v[72:75]
	v_mfma_f32_16x16x32_bf16 v[64:67], v[174:177], v[214:217], v[64:67]
	s_setprio 0
	s_barrier
; #define PG8_STAGE(bufoff, gbase, voff) do { _Pragma("unroll") for (int _i = 0; _i < 2; ++_i) \
;         __builtin_amdgcn_global_load_lds((const unsigned*)((const char*)(gbase) + (voff)[_i]), (PG8_LAS unsigned*)(lds + (bufoff) + ldsw + _i * 8192), 16, 0, 0); } while (0)
; #define PG8_LDA(dst, b, h) do { _Pragma("unroll") for (int m = 0; m < 4; ++m) _Pragma("unroll") for (int k = 0; k < 2; ++k) dst[m][k] = *(const PG8_LAS bf16x8*)(lds + PG8_SA(b, h) + aoff + m * 2048 + k * 1024); } while (0)
; #define PG8_MMA(ai, bj, At, Bt) do { __builtin_amdgcn_s_setprio(1); _Pragma("unroll") for (int m = 0; m < 4; ++m) _Pragma("unroll") for (int n = 0; n < 2; ++n) _Pragma("unroll") for (int k = 0; k < 2; ++k) \
;         acc[ai][bj][m][n] = __builtin_amdgcn_mfma_f32_16x16x32_bf16(Bt[n][k], At[m][k], acc[ai][bj][m][n], 0, 0, 0); __builtin_amdgcn_s_setprio(0); } while (0)
; #define PG8_WAIT_V(n) asm volatile("s_waitcnt vmcnt(" #n ")" ::: "memory")
; #define PG8_WAIT_L(n) asm volatile("s_waitcnt lgkmcnt(" #n ")" ::: "memory")
; #define PG8_BAR __builtin_amdgcn_s_barrier()
; #define PG8_SCHED __builtin_amdgcn_sched_barrier(0)
; template <class Epi, class Sched, bool ALIGN_EPI = false, bool SP2 = false>
; __device__ __forceinline__ void gemm_phase(PG8_LAS unsigned char* lds, const Gemm g, const Sched& S, const Epi& E) {
;     ...
;             PG8_LDA(At, 1, 1); PG8_STAGE(PG8_SB(1, 0), b3, voffB); PG8_STAGE(PG8_SB(1, 1), b3 + hstep, voffB); PG8_STAGE(PG8_SA(1, 0), a3, voffA);
;             PG8_WAIT_V(8); PG8_WAIT_L(0); PG8_BAR; PG8_MMA(1, 0, At, B0); PG8_MMA(1, 1, At, B1); PG8_BAR; PG8_SCHED;
	s_add_i32 s12, s24, s30
	v_lshl_add_u64 v[190:191], v[190:191], 0, s[16:17]
	s_mov_b32 m0, s12
	ds_read_b128 v[178:181], v152 offset:49152
	ds_read_b128 v[182:185], v152 offset:50176
	ds_read_b128 v[186:189], v152 offset:51200
	ds_read_b128 v[194:197], v152 offset:52224
	ds_read_b128 v[202:205], v152 offset:53248
	ds_read_b128 v[206:209], v152 offset:54272
	ds_read_b128 v[210:213], v152 offset:55296
	ds_read_b128 v[214:217], v152 offset:56320
	global_load_lds_dwordx4 v[190:191], off
	s_add_i32 m0, s12, 0x2000
	s_add_u32 s10, s10, 0x80080
	v_lshl_add_u64 v[190:191], v[218:219], 0, s[16:17]
	s_addc_u32 s11, s11, 0
	s_add_i32 s12, s25, s30
	global_load_lds_dwordx4 v[190:191], off
	s_mov_b32 m0, s12
	v_lshl_add_u64 v[190:191], s[10:11], 0, v[132:133]
	global_load_lds_dwordx4 v[190:191], off
	s_add_i32 m0, s12, 0x2000
	v_lshl_add_u64 v[190:191], s[10:11], 0, v[128:129]
	global_load_lds_dwordx4 v[190:191], off
	s_mov_b32 m0, s56
	v_lshl_add_u64 v[190:191], v[220:221], 0, s[16:17]
	global_load_lds_dwordx4 v[190:191], off
	s_mov_b32 m0, s57
	v_lshl_add_u64 v[190:191], v[230:231], 0, s[16:17]
	global_load_lds_dwordx4 v[190:191], off
	s_waitcnt vmcnt(8)
	s_waitcnt lgkmcnt(0)
	s_barrier
	s_setprio 1
	s_waitcnt lgkmcnt(0)
	v_mfma_f32_16x16x32_bf16 v[60:63], v[140:143], v[178:181], v[60:63]
	v_mfma_f32_16x16x32_bf16 v[52:55], v[154:157], v[178:181], v[52:55]
	v_mfma_f32_16x16x32_bf16 v[44:47], v[140:143], v[186:189], v[44:47]
	v_mfma_f32_16x16x32_bf16 v[36:39], v[154:157], v[186:189], v[36:39]
	v_mfma_f32_16x16x32_bf16 v[28:31], v[140:143], v[202:205], v[28:31]
	v_mfma_f32_16x16x32_bf16 v[20:23], v[154:157], v[202:205], v[20:23]
	v_mfma_f32_16x16x32_bf16 v[12:15], v[140:143], v[210:213], v[12:15]
	v_mfma_f32_16x16x32_bf16 v[4:7], v[154:157], v[210:213], v[4:7]
	v_mfma_f32_16x16x32_bf16 v[60:63], v[144:147], v[182:185], v[60:63]
	v_mfma_f32_16x16x32_bf16 v[52:55], v[158:161], v[182:185], v[52:55]
	v_mfma_f32_16x16x32_bf16 v[44:47], v[144:147], v[194:197], v[44:47]
	v_mfma_f32_16x16x32_bf16 v[36:39], v[158:161], v[194:197], v[36:39]
	v_mfma_f32_16x16x32_bf16 v[28:31], v[144:147], v[206:209], v[28:31]
	v_mfma_f32_16x16x32_bf16 v[20:23], v[158:161], v[206:209], v[20:23]
	v_mfma_f32_16x16x32_bf16 v[12:15], v[144:147], v[214:217], v[12:15]
	v_mfma_f32_16x16x32_bf16 v[4:7], v[158:161], v[214:217], v[4:7]
	s_setprio 0
	s_setprio 1
	v_mfma_f32_16x16x32_bf16 v[56:59], v[162:165], v[178:181], v[56:59]
	v_mfma_f32_16x16x32_bf16 v[48:51], v[170:173], v[178:181], v[48:51]
	v_mfma_f32_16x16x32_bf16 v[40:43], v[162:165], v[186:189], v[40:43]
	v_mfma_f32_16x16x32_bf16 v[32:35], v[170:173], v[186:189], v[32:35]
	v_mfma_f32_16x16x32_bf16 v[24:27], v[162:165], v[202:205], v[24:27]
	v_mfma_f32_16x16x32_bf16 v[16:19], v[170:173], v[202:205], v[16:19]
	v_mfma_f32_16x16x32_bf16 v[8:11], v[162:165], v[210:213], v[8:11]
	v_mfma_f32_16x16x32_bf16 v[0:3], v[170:173], v[210:213], v[0:3]
	v_mfma_f32_16x16x32_bf16 v[56:59], v[166:169], v[182:185], v[56:59]
	v_mfma_f32_16x16x32_bf16 v[48:51], v[174:177], v[182:185], v[48:51]
	v_mfma_f32_16x16x32_bf16 v[40:43], v[166:169], v[194:197], v[40:43]
	v_mfma_f32_16x16x32_bf16 v[32:35], v[174:177], v[194:197], v[32:35]
	v_mfma_f32_16x16x32_bf16 v[24:27], v[166:169], v[206:209], v[24:27]
	v_mfma_f32_16x16x32_bf16 v[16:19], v[174:177], v[206:209], v[16:19]
	v_mfma_f32_16x16x32_bf16 v[8:11], v[166:169], v[214:217], v[8:11]
	v_mfma_f32_16x16x32_bf16 v[0:3], v[174:177], v[214:217], v[0:3]
	s_setprio 0
	s_barrier
	s_add_i32 s64, s64, 2
	s_add_u32 s0, s0, 0x100
	s_addc_u32 s1, s1, 0
	s_add_u32 s62, s62, 0x100
	s_addc_u32 s63, s63, 0
	s_cmp_gt_u32 s64, 29
	s_branch .LBB0_730

; #define PG8_STAGE(bufoff, gbase, voff) do { _Pragma("unroll") for (int _i = 0; _i < 2; ++_i) \
;         __builtin_amdgcn_global_load_lds((const unsigned*)((const char*)(gbase) + (voff)[_i]), (PG8_LAS unsigned*)(lds + (bufoff) + ldsw + _i * 8192), 16, 0, 0); } while (0)
; #define PG8_LDA(dst, b, h) do { _Pragma("unroll") for (int m = 0; m < 4; ++m) _Pragma("unroll") for (int k = 0; k < 2; ++k) dst[m][k] = *(const PG8_LAS bf16x8*)(lds + PG8_SA(b, h) + aoff + m * 2048 + k * 1024); } while (0)
; #define PG8_WAIT_V(n) asm volatile("s_waitcnt vmcnt(" #n ")" ::: "memory")
; #define PG8_WAIT_L(n) asm volatile("s_waitcnt lgkmcnt(" #n ")" ::: "memory")
; template <class Epi, class Sched, bool ALIGN_EPI = false, bool SP2 = false>
; __device__ __forceinline__ void gemm_phase(PG8_LAS unsigned char* lds, const Gemm g, const Sched& S, const Epi& E) {
;     ...
;         const bool has_next = S.next(ui + 1, nxt);
;         const char* nA = has_next ? (const char*)g.A + (size_t)nxt.pm * tstep : cA; const char* nB = has_next ? (const char*)g.Bt + (size_t)nxt.pn * tstep : cB;
;         for (int t = 0; t < nt; t += 2) {
;             if constexpr (Epi::MID_HOOK) { if (t == Epi::MID_T) E.mid(acc, cur, wr, wc, fr, fq); }
;             const bool last = (t == nt - 2);
;             const char* a1 = cA + (size_t)(t + 1) * kstep;
;             const char* a2 = last ? nA : cA + (size_t)(t + 2) * kstep; const char* b2 = last ? nB : cB + (size_t)(t + 2) * kstep;
;             const char* a3 = a2 + kstep; const char* b3 = b2 + kstep;
;             if (last && has_next) S.a_ready(nxt);
;             if constexpr (SP2) {
;             PG8_LDB(B0, 0, 0); PG8_LDB(B1, 0, 1); PG8_SCHED; PG8_LDA(At, 0, 0); PG8_STAGE(PG8_SA(1, 1), a1 + hstep, voffA);
;             PG8_WAIT_V(8); PG8_WAIT_L(0); PG8_BAR; PG8_MMA(0, 0, At, B0); PG8_MMA(0, 1, At, B1); PG8_BAR; PG8_SCHED;
;             PG8_LDA(At, 0, 1); PG8_STAGE(PG8_SB(0, 0), b2, voffB); PG8_STAGE(PG8_SB(0, 1), b2 + hstep, voffB); PG8_STAGE(PG8_SA(0, 0), a2, voffA);
;             PG8_WAIT_V(8); PG8_WAIT_L(0); PG8_BAR; PG8_MMA(1, 0, At, B0); PG8_MMA(1, 1, At, B1); PG8_BAR; PG8_SCHED;
;     ...
;         for (int a = 0; a < 2; ++a)
; #pragma unroll
;             for (int b = 0; b < 2; ++b)
; #pragma unroll
;                 for (int m = 0; m < 4; ++m)
; #pragma unroll
;                     for (int n = 0; n < 2; ++n) acc[a][b][m][n] = (f32x4){0.f, 0.f, 0.f, 0.f};
.LBB0_816:
	s_add_u32 s59, s30, 0x100
	s_addc_u32 s60, s31, 0
	s_mov_b32 s61, -2
	s_waitcnt lgkmcnt(0)
	v_add_u32_e32 v140, 0x10000, v172
	v_add_u32_e32 v168, 0x14000, v172
	ds_read_b128 v[128:131], v140
	ds_read_b128 v[132:135], v140 offset:1024
	ds_read_b128 v[136:139], v140 offset:2048
	ds_read_b128 v[140:143], v140 offset:3072
	ds_read_b128 v[144:147], v168
	ds_read_b128 v[148:151], v168 offset:1024
	ds_read_b128 v[164:167], v168 offset:2048
	ds_read_b128 v[174:177], v168 offset:3072
	v_lshl_add_u64 v[168:169], s[18:19], 0, v[160:161]
	s_add_i32 m0, s2, 0xc000
	ds_read_b128 v[178:181], v173
	ds_read_b128 v[182:185], v173 offset:1024
	ds_read_b128 v[186:189], v173 offset:2048
	ds_read_b128 v[194:197], v173 offset:3072
	ds_read_b128 v[202:205], v173 offset:4096
	ds_read_b128 v[206:209], v173 offset:5120
	ds_read_b128 v[210:213], v173 offset:6144
	ds_read_b128 v[214:217], v173 offset:7168
	global_load_lds_dwordx4 v[168:169], off
	s_add_i32 m0, s2, 0xe000
	v_lshl_add_u64 v[168:169], s[18:19], 0, v[162:163]
	global_load_lds_dwordx4 v[168:169], off
	s_add_u32 s30, s18, 0x100
	s_addc_u32 s31, s19, 0
	s_add_i32 s24, 0, 0x10000
	s_cmpk_eq_i32 s61, 0x54
	s_cselect_b32 s39, s5, s31
	s_cselect_b32 s38, s4, s30
	s_cselect_b32 s37, s15, s60
	s_cselect_b32 s36, s14, s59
	s_add_i32 s25, 0, 0x14000
	s_waitcnt vmcnt(8)
	s_waitcnt lgkmcnt(0)
	s_barrier
	s_setprio 1
	s_waitcnt lgkmcnt(0)
	v_mfma_f32_16x16x32_bf16 v[124:127], v[128:131], v[178:181], 0
	v_mfma_f32_16x16x32_bf16 v[120:123], v[136:139], v[178:181], 0
	v_mfma_f32_16x16x32_bf16 v[108:111], v[128:131], v[186:189], 0
	v_mfma_f32_16x16x32_bf16 v[104:107], v[136:139], v[186:189], 0
	v_mfma_f32_16x16x32_bf16 v[92:95], v[128:131], v[202:205], 0
	v_mfma_f32_16x16x32_bf16 v[88:91], v[136:139], v[202:205], 0
	v_mfma_f32_16x16x32_bf16 v[76:79], v[128:131], v[210:213], 0
	v_mfma_f32_16x16x32_bf16 v[72:75], v[136:139], v[210:213], 0
	v_mfma_f32_16x16x32_bf16 v[124:127], v[132:135], v[182:185], v[124:127]
	v_mfma_f32_16x16x32_bf16 v[120:123], v[140:143], v[182:185], v[120:123]
	v_mfma_f32_16x16x32_bf16 v[108:111], v[132:135], v[194:197], v[108:111]
	v_mfma_f32_16x16x32_bf16 v[104:107], v[140:143], v[194:197], v[104:107]
	v_mfma_f32_16x16x32_bf16 v[92:95], v[132:135], v[206:209], v[92:95]
	v_mfma_f32_16x16x32_bf16 v[88:91], v[140:143], v[206:209], v[88:91]
	v_mfma_f32_16x16x32_bf16 v[76:79], v[132:135], v[214:217], v[76:79]
	v_mfma_f32_16x16x32_bf16 v[72:75], v[140:143], v[214:217], v[72:75]
	s_setprio 0
	s_setprio 1
	v_mfma_f32_16x16x32_bf16 v[116:119], v[144:147], v[178:181], 0
	v_mfma_f32_16x16x32_bf16 v[112:115], v[164:167], v[178:181], 0
	v_mfma_f32_16x16x32_bf16 v[100:103], v[144:147], v[186:189], 0
	v_mfma_f32_16x16x32_bf16 v[96:99], v[164:167], v[186:189], 0
	v_mfma_f32_16x16x32_bf16 v[84:87], v[144:147], v[202:205], 0
	v_mfma_f32_16x16x32_bf16 v[80:83], v[164:167], v[202:205], 0
	v_mfma_f32_16x16x32_bf16 v[68:71], v[144:147], v[210:213], 0
	v_mfma_f32_16x16x32_bf16 v[64:67], v[164:167], v[210:213], 0
	v_mfma_f32_16x16x32_bf16 v[116:119], v[148:151], v[182:185], v[116:119]
	v_mfma_f32_16x16x32_bf16 v[112:115], v[174:177], v[182:185], v[112:115]
	v_mfma_f32_16x16x32_bf16 v[100:103], v[148:151], v[194:197], v[100:103]
	v_mfma_f32_16x16x32_bf16 v[96:99], v[174:177], v[194:197], v[96:99]
	v_mfma_f32_16x16x32_bf16 v[84:87], v[148:151], v[206:209], v[84:87]
	v_mfma_f32_16x16x32_bf16 v[80:83], v[174:177], v[206:209], v[80:83]
	v_mfma_f32_16x16x32_bf16 v[68:71], v[148:151], v[214:217], v[68:71]
	v_mfma_f32_16x16x32_bf16 v[64:67], v[174:177], v[214:217], v[64:67]
	s_setprio 0
	s_barrier
	s_add_i32 s18, s24, s43
	v_lshl_add_u64 v[168:169], s[36:37], 0, v[156:157]
	s_mov_b32 m0, s18
	ds_read_b128 v[178:181], v173 offset:16384
	ds_read_b128 v[182:185], v173 offset:17408
	ds_read_b128 v[186:189], v173 offset:18432
	ds_read_b128 v[194:197], v173 offset:19456
	ds_read_b128 v[202:205], v173 offset:20480
	ds_read_b128 v[206:209], v173 offset:21504
	ds_read_b128 v[210:213], v173 offset:22528
	ds_read_b128 v[214:217], v173 offset:23552
	global_load_lds_dwordx4 v[168:169], off
	s_add_i32 m0, s18, 0x2000
	s_add_u32 s18, s36, 0x160000
	v_lshl_add_u64 v[190:191], s[36:37], 0, v[152:153]
	s_addc_u32 s19, s37, 0
	s_add_i32 s24, s25, s43
	global_load_lds_dwordx4 v[190:191], off
	v_lshl_add_u64 v[218:219], s[18:19], 0, v[156:157]
	s_mov_b32 m0, s24
	v_lshl_add_u64 v[220:221], s[38:39], 0, v[154:155]
	global_load_lds_dwordx4 v[218:219], off
	s_add_i32 m0, s24, 0x2000
	v_lshl_add_u64 v[218:219], s[18:19], 0, v[152:153]
	global_load_lds_dwordx4 v[218:219], off
	s_mov_b32 m0, s2
	v_lshl_add_u64 v[218:219], s[38:39], 0, v[158:159]
	global_load_lds_dwordx4 v[218:219], off
	s_mov_b32 m0, s44
	s_nop 0
	global_load_lds_dwordx4 v[220:221], off
	s_waitcnt vmcnt(8)
	s_waitcnt lgkmcnt(0)
	s_barrier
; #define PG8_STAGE(bufoff, gbase, voff) do { _Pragma("unroll") for (int _i = 0; _i < 2; ++_i) \
;         __builtin_amdgcn_global_load_lds((const unsigned*)((const char*)(gbase) + (voff)[_i]), (PG8_LAS unsigned*)(lds + (bufoff) + ldsw + _i * 8192), 16, 0, 0); } while (0)
; #define PG8_LDA(dst, b, h) do { _Pragma("unroll") for (int m = 0; m < 4; ++m) _Pragma("unroll") for (int k = 0; k < 2; ++k) dst[m][k] = *(const PG8_LAS bf16x8*)(lds + PG8_SA(b, h) + aoff + m * 2048 + k * 1024); } while (0)
; #define PG8_LDB(dst, b, h) do { _Pragma("unroll") for (int n = 0; n < 2; ++n) _Pragma("unroll") for (int k = 0; k < 2; ++k) dst[n][k] = *(const PG8_LAS bf16x8*)(lds + PG8_SB(b, h) + boff + n * 2048 + k * 1024); } while (0)
; #define PG8_MMA(ai, bj, At, Bt) do { __builtin_amdgcn_s_setprio(1); _Pragma("unroll") for (int m = 0; m < 4; ++m) _Pragma("unroll") for (int n = 0; n < 2; ++n) _Pragma("unroll") for (int k = 0; k < 2; ++k) \
;         acc[ai][bj][m][n] = __builtin_amdgcn_mfma_f32_16x16x32_bf16(Bt[n][k], At[m][k], acc[ai][bj][m][n], 0, 0, 0); __builtin_amdgcn_s_setprio(0); } while (0)
; #define PG8_WAIT_V(n) asm volatile("s_waitcnt vmcnt(" #n ")" ::: "memory")
; #define PG8_WAIT_L(n) asm volatile("s_waitcnt lgkmcnt(" #n ")" ::: "memory")
; #define PG8_BAR __builtin_amdgcn_s_barrier()
; #define PG8_SCHED __builtin_amdgcn_sched_barrier(0)
; template <class Epi, class Sched, bool ALIGN_EPI = false, bool SP2 = false>
; __device__ __forceinline__ void gemm_phase(PG8_LAS unsigned char* lds, const Gemm g, const Sched& S, const Epi& E) {
;     ...
;             PG8_WAIT_V(8); PG8_WAIT_L(0); PG8_BAR; PG8_MMA(1, 0, At, B0); PG8_MMA(1, 1, At, B1); PG8_BAR; PG8_SCHED;
;             PG8_LDB(B0, 1, 0); PG8_LDB(B1, 1, 1); PG8_SCHED; PG8_LDA(At, 1, 0); PG8_STAGE(PG8_SA(0, 1), a2 + hstep, voffA);
;             PG8_WAIT_V(8); PG8_WAIT_L(0); PG8_BAR; PG8_MMA(0, 0, At, B0); PG8_MMA(0, 1, At, B1); PG8_BAR; PG8_SCHED;
	s_setprio 1
	s_waitcnt lgkmcnt(0)
	v_mfma_f32_16x16x32_bf16 v[60:63], v[128:131], v[178:181], 0
	v_mfma_f32_16x16x32_bf16 v[56:59], v[136:139], v[178:181], 0
	v_mfma_f32_16x16x32_bf16 v[44:47], v[128:131], v[186:189], 0
	v_mfma_f32_16x16x32_bf16 v[40:43], v[136:139], v[186:189], 0
	v_mfma_f32_16x16x32_bf16 v[28:31], v[128:131], v[202:205], 0
	v_mfma_f32_16x16x32_bf16 v[24:27], v[136:139], v[202:205], 0
	v_mfma_f32_16x16x32_bf16 v[12:15], v[128:131], v[210:213], 0
	v_mfma_f32_16x16x32_bf16 v[8:11], v[136:139], v[210:213], 0
	v_mfma_f32_16x16x32_bf16 v[60:63], v[132:135], v[182:185], v[60:63]
	v_mfma_f32_16x16x32_bf16 v[56:59], v[140:143], v[182:185], v[56:59]
	v_mfma_f32_16x16x32_bf16 v[44:47], v[132:135], v[194:197], v[44:47]
	v_mfma_f32_16x16x32_bf16 v[40:43], v[140:143], v[194:197], v[40:43]
	v_mfma_f32_16x16x32_bf16 v[28:31], v[132:135], v[206:209], v[28:31]
	v_mfma_f32_16x16x32_bf16 v[24:27], v[140:143], v[206:209], v[24:27]
	v_mfma_f32_16x16x32_bf16 v[12:15], v[132:135], v[214:217], v[12:15]
	v_mfma_f32_16x16x32_bf16 v[8:11], v[140:143], v[214:217], v[8:11]
	s_setprio 0
	s_setprio 1
	v_mfma_f32_16x16x32_bf16 v[52:55], v[144:147], v[178:181], 0
	v_mfma_f32_16x16x32_bf16 v[48:51], v[164:167], v[178:181], 0
	v_mfma_f32_16x16x32_bf16 v[36:39], v[144:147], v[186:189], 0
	v_mfma_f32_16x16x32_bf16 v[32:35], v[164:167], v[186:189], 0
	v_mfma_f32_16x16x32_bf16 v[20:23], v[144:147], v[202:205], 0
	v_mfma_f32_16x16x32_bf16 v[16:19], v[164:167], v[202:205], 0
	v_mfma_f32_16x16x32_bf16 v[4:7], v[144:147], v[210:213], 0
	v_mfma_f32_16x16x32_bf16 v[0:3], v[164:167], v[210:213], 0
	v_mfma_f32_16x16x32_bf16 v[52:55], v[148:151], v[182:185], v[52:55]
	v_mfma_f32_16x16x32_bf16 v[48:51], v[174:177], v[182:185], v[48:51]
	v_mfma_f32_16x16x32_bf16 v[36:39], v[148:151], v[194:197], v[36:39]
	v_mfma_f32_16x16x32_bf16 v[32:35], v[174:177], v[194:197], v[32:35]
	v_mfma_f32_16x16x32_bf16 v[20:23], v[148:151], v[206:209], v[20:23]
	v_mfma_f32_16x16x32_bf16 v[16:19], v[174:177], v[206:209], v[16:19]
	v_mfma_f32_16x16x32_bf16 v[4:7], v[148:151], v[214:217], v[4:7]
	v_mfma_f32_16x16x32_bf16 v[0:3], v[174:177], v[214:217], v[0:3]
	s_setprio 0
	s_barrier
	s_add_i32 s24, 0, 0x18000
	s_add_i32 s25, 0, 0x1c000
	v_add_u32_e32 v140, 0x18000, v172
	v_add_u32_e32 v174, 0x1c000, v172
	ds_read_b128 v[128:131], v140
	ds_read_b128 v[132:135], v140 offset:1024
	ds_read_b128 v[136:139], v140 offset:2048
	ds_read_b128 v[140:143], v140 offset:3072
	ds_read_b128 v[144:147], v174
	ds_read_b128 v[148:151], v174 offset:1024
	ds_read_b128 v[164:167], v174 offset:2048
	ds_read_b128 v[174:177], v174 offset:3072
	s_add_u32 s18, s38, 0x160000
	s_addc_u32 s19, s39, 0
	s_mov_b32 m0, s45
	v_lshl_add_u64 v[230:231], s[18:19], 0, v[158:159]
	ds_read_b128 v[178:181], v173 offset:32768
	ds_read_b128 v[182:185], v173 offset:33792
	ds_read_b128 v[186:189], v173 offset:34816
	ds_read_b128 v[194:197], v173 offset:35840
	ds_read_b128 v[202:205], v173 offset:36864
	ds_read_b128 v[206:209], v173 offset:37888
	ds_read_b128 v[210:213], v173 offset:38912
	ds_read_b128 v[214:217], v173 offset:39936
	global_load_lds_dwordx4 v[230:231], off
	s_mov_b32 m0, s46
	v_lshl_add_u64 v[230:231], s[18:19], 0, v[154:155]
	global_load_lds_dwordx4 v[230:231], off
	s_waitcnt vmcnt(8)
	s_waitcnt lgkmcnt(0)
	s_barrier
	s_setprio 1
	s_waitcnt lgkmcnt(0)
	v_mfma_f32_16x16x32_bf16 v[124:127], v[128:131], v[178:181], v[124:127]
	v_mfma_f32_16x16x32_bf16 v[120:123], v[136:139], v[178:181], v[120:123]
	v_mfma_f32_16x16x32_bf16 v[108:111], v[128:131], v[186:189], v[108:111]
	v_mfma_f32_16x16x32_bf16 v[104:107], v[136:139], v[186:189], v[104:107]
	v_mfma_f32_16x16x32_bf16 v[92:95], v[128:131], v[202:205], v[92:95]
	v_mfma_f32_16x16x32_bf16 v[88:91], v[136:139], v[202:205], v[88:91]
	v_mfma_f32_16x16x32_bf16 v[76:79], v[128:131], v[210:213], v[76:79]
	v_mfma_f32_16x16x32_bf16 v[72:75], v[136:139], v[210:213], v[72:75]
	v_mfma_f32_16x16x32_bf16 v[124:127], v[132:135], v[182:185], v[124:127]
	v_mfma_f32_16x16x32_bf16 v[120:123], v[140:143], v[182:185], v[120:123]
	v_mfma_f32_16x16x32_bf16 v[108:111], v[132:135], v[194:197], v[108:111]
	v_mfma_f32_16x16x32_bf16 v[104:107], v[140:143], v[194:197], v[104:107]
	v_mfma_f32_16x16x32_bf16 v[92:95], v[132:135], v[206:209], v[92:95]
	v_mfma_f32_16x16x32_bf16 v[88:91], v[140:143], v[206:209], v[88:91]
	v_mfma_f32_16x16x32_bf16 v[76:79], v[132:135], v[214:217], v[76:79]
	v_mfma_f32_16x16x32_bf16 v[72:75], v[140:143], v[214:217], v[72:75]
	s_setprio 0
	s_setprio 1
	v_mfma_f32_16x16x32_bf16 v[116:119], v[144:147], v[178:181], v[116:119]
	v_mfma_f32_16x16x32_bf16 v[112:115], v[164:167], v[178:181], v[112:115]
	v_mfma_f32_16x16x32_bf16 v[100:103], v[144:147], v[186:189], v[100:103]
	v_mfma_f32_16x16x32_bf16 v[96:99], v[164:167], v[186:189], v[96:99]
	v_mfma_f32_16x16x32_bf16 v[84:87], v[144:147], v[202:205], v[84:87]
	v_mfma_f32_16x16x32_bf16 v[80:83], v[164:167], v[202:205], v[80:83]
	v_mfma_f32_16x16x32_bf16 v[68:71], v[144:147], v[210:213], v[68:71]
	v_mfma_f32_16x16x32_bf16 v[64:67], v[164:167], v[210:213], v[64:67]
	v_mfma_f32_16x16x32_bf16 v[116:119], v[148:151], v[182:185], v[116:119]
	v_mfma_f32_16x16x32_bf16 v[112:115], v[174:177], v[182:185], v[112:115]
	v_mfma_f32_16x16x32_bf16 v[100:103], v[148:151], v[194:197], v[100:103]
	v_mfma_f32_16x16x32_bf16 v[96:99], v[174:177], v[194:197], v[96:99]
	v_mfma_f32_16x16x32_bf16 v[84:87], v[148:151], v[206:209], v[84:87]
	v_mfma_f32_16x16x32_bf16 v[80:83], v[174:177], v[206:209], v[80:83]
	v_mfma_f32_16x16x32_bf16 v[68:71], v[148:151], v[214:217], v[68:71]
	v_mfma_f32_16x16x32_bf16 v[64:67], v[174:177], v[214:217], v[64:67]
	s_setprio 0
	s_barrier
; #define PG8_STAGE(bufoff, gbase, voff) do { _Pragma("unroll") for (int _i = 0; _i < 2; ++_i) \
;         __builtin_amdgcn_global_load_lds((const unsigned*)((const char*)(gbase) + (voff)[_i]), (PG8_LAS unsigned*)(lds + (bufoff) + ldsw + _i * 8192), 16, 0, 0); } while (0)
; #define PG8_LDA(dst, b, h) do { _Pragma("unroll") for (int m = 0; m < 4; ++m) _Pragma("unroll") for (int k = 0; k < 2; ++k) dst[m][k] = *(const PG8_LAS bf16x8*)(lds + PG8_SA(b, h) + aoff + m * 2048 + k * 1024); } while (0)
; #define PG8_MMA(ai, bj, At, Bt) do { __builtin_amdgcn_s_setprio(1); _Pragma("unroll") for (int m = 0; m < 4; ++m) _Pragma("unroll") for (int n = 0; n < 2; ++n) _Pragma("unroll") for (int k = 0; k < 2; ++k) \
;         acc[ai][bj][m][n] = __builtin_amdgcn_mfma_f32_16x16x32_bf16(Bt[n][k], At[m][k], acc[ai][bj][m][n], 0, 0, 0); __builtin_amdgcn_s_setprio(0); } while (0)
; #define PG8_WAIT_V(n) asm volatile("s_waitcnt vmcnt(" #n ")" ::: "memory")
; #define PG8_WAIT_L(n) asm volatile("s_waitcnt lgkmcnt(" #n ")" ::: "memory")
; #define PG8_BAR __builtin_amdgcn_s_barrier()
; #define PG8_SCHED __builtin_amdgcn_sched_barrier(0)
; template <class Epi, class Sched, bool ALIGN_EPI = false, bool SP2 = false>
; __device__ __forceinline__ void gemm_phase(PG8_LAS unsigned char* lds, const Gemm g, const Sched& S, const Epi& E) {
;     ...
;             PG8_LDA(At, 1, 1); PG8_STAGE(PG8_SB(1, 0), b3, voffB); PG8_STAGE(PG8_SB(1, 1), b3 + hstep, voffB); PG8_STAGE(PG8_SA(1, 0), a3, voffA);
;             PG8_WAIT_V(8); PG8_WAIT_L(0); PG8_BAR; PG8_MMA(1, 0, At, B0); PG8_MMA(1, 1, At, B1); PG8_BAR; PG8_SCHED;
	s_add_i32 s18, s24, s43
	v_lshl_add_u64 v[168:169], v[168:169], 0, s[16:17]
	s_mov_b32 m0, s18
	ds_read_b128 v[178:181], v173 offset:49152
	ds_read_b128 v[182:185], v173 offset:50176
	ds_read_b128 v[186:189], v173 offset:51200
	ds_read_b128 v[194:197], v173 offset:52224
	ds_read_b128 v[202:205], v173 offset:53248
	ds_read_b128 v[206:209], v173 offset:54272
	ds_read_b128 v[210:213], v173 offset:55296
	ds_read_b128 v[214:217], v173 offset:56320
	global_load_lds_dwordx4 v[168:169], off
	s_add_i32 m0, s18, 0x2000
	s_add_u32 s18, s36, 0x160080
	v_lshl_add_u64 v[168:169], v[190:191], 0, s[16:17]
	s_addc_u32 s19, s37, 0
	s_add_i32 s24, s25, s43
	global_load_lds_dwordx4 v[168:169], off
	s_mov_b32 m0, s24
	v_lshl_add_u64 v[168:169], s[18:19], 0, v[156:157]
	global_load_lds_dwordx4 v[168:169], off
	s_add_i32 m0, s24, 0x2000
	v_lshl_add_u64 v[168:169], s[18:19], 0, v[152:153]
	global_load_lds_dwordx4 v[168:169], off
	s_mov_b32 m0, s51
	v_lshl_add_u64 v[168:169], v[218:219], 0, s[16:17]
	global_load_lds_dwordx4 v[168:169], off
	s_mov_b32 m0, s52
	v_lshl_add_u64 v[168:169], v[220:221], 0, s[16:17]
	global_load_lds_dwordx4 v[168:169], off
	s_waitcnt vmcnt(8)
	s_waitcnt lgkmcnt(0)
	s_barrier
	s_setprio 1
	s_waitcnt lgkmcnt(0)
	v_mfma_f32_16x16x32_bf16 v[60:63], v[128:131], v[178:181], v[60:63]
	v_mfma_f32_16x16x32_bf16 v[56:59], v[136:139], v[178:181], v[56:59]
	v_mfma_f32_16x16x32_bf16 v[44:47], v[128:131], v[186:189], v[44:47]
	v_mfma_f32_16x16x32_bf16 v[40:43], v[136:139], v[186:189], v[40:43]
	v_mfma_f32_16x16x32_bf16 v[28:31], v[128:131], v[202:205], v[28:31]
	v_mfma_f32_16x16x32_bf16 v[24:27], v[136:139], v[202:205], v[24:27]
	v_mfma_f32_16x16x32_bf16 v[12:15], v[128:131], v[210:213], v[12:15]
	v_mfma_f32_16x16x32_bf16 v[8:11], v[136:139], v[210:213], v[8:11]
	v_mfma_f32_16x16x32_bf16 v[60:63], v[132:135], v[182:185], v[60:63]
	v_mfma_f32_16x16x32_bf16 v[56:59], v[140:143], v[182:185], v[56:59]
	v_mfma_f32_16x16x32_bf16 v[44:47], v[132:135], v[194:197], v[44:47]
	v_mfma_f32_16x16x32_bf16 v[40:43], v[140:143], v[194:197], v[40:43]
	v_mfma_f32_16x16x32_bf16 v[28:31], v[132:135], v[206:209], v[28:31]
	v_mfma_f32_16x16x32_bf16 v[24:27], v[140:143], v[206:209], v[24:27]
	v_mfma_f32_16x16x32_bf16 v[12:15], v[132:135], v[214:217], v[12:15]
	v_mfma_f32_16x16x32_bf16 v[8:11], v[140:143], v[214:217], v[8:11]
	s_setprio 0
	s_setprio 1
	v_mfma_f32_16x16x32_bf16 v[52:55], v[144:147], v[178:181], v[52:55]
	v_mfma_f32_16x16x32_bf16 v[48:51], v[164:167], v[178:181], v[48:51]
	v_mfma_f32_16x16x32_bf16 v[36:39], v[144:147], v[186:189], v[36:39]
	v_mfma_f32_16x16x32_bf16 v[32:35], v[164:167], v[186:189], v[32:35]
	v_mfma_f32_16x16x32_bf16 v[20:23], v[144:147], v[202:205], v[20:23]
	v_mfma_f32_16x16x32_bf16 v[16:19], v[164:167], v[202:205], v[16:19]
	v_mfma_f32_16x16x32_bf16 v[4:7], v[144:147], v[210:213], v[4:7]
	v_mfma_f32_16x16x32_bf16 v[0:3], v[164:167], v[210:213], v[0:3]
	v_mfma_f32_16x16x32_bf16 v[52:55], v[148:151], v[182:185], v[52:55]
	v_mfma_f32_16x16x32_bf16 v[48:51], v[174:177], v[182:185], v[48:51]
	v_mfma_f32_16x16x32_bf16 v[36:39], v[148:151], v[194:197], v[36:39]
	v_mfma_f32_16x16x32_bf16 v[32:35], v[174:177], v[194:197], v[32:35]
	v_mfma_f32_16x16x32_bf16 v[20:23], v[148:151], v[206:209], v[20:23]
	v_mfma_f32_16x16x32_bf16 v[16:19], v[174:177], v[206:209], v[16:19]
	v_mfma_f32_16x16x32_bf16 v[4:7], v[148:151], v[214:217], v[4:7]
	v_mfma_f32_16x16x32_bf16 v[0:3], v[174:177], v[214:217], v[0:3]
	s_setprio 0
	s_barrier
	s_add_i32 s61, s61, 2
	s_add_u32 s59, s59, 0x100
	s_addc_u32 s60, s60, 0
	s_cmpk_gt_u32 s61, 0x55
	s_mov_b64 s[18:19], s[30:31]
	s_branch .LBB0_817
